# phase 4 epilogues: gate/M loads two 16-token blocks ahead (three load buffers) instead of one
# baseline (speedup 1.0000x reference)
; #define PG8_STAGE(bufoff, gbase, voff) do { _Pragma("unroll") for (int _i = 0; _i < 2; ++_i) \
;         __builtin_amdgcn_global_load_lds((const unsigned*)((const char*)(gbase) + (voff)[_i]), (PG8_LAS unsigned*)(lds + (bufoff) + ldsw + _i * 8192), 16, 0, 0); } while (0)
; #define PG8_LDA(dst, b, h) do { _Pragma("unroll") for (int m = 0; m < 4; ++m) _Pragma("unroll") for (int k = 0; k < 2; ++k) dst[m][k] = *(const PG8_LAS bf16x8*)(lds + PG8_SA(b, h) + aoff + m * 2048 + k * 1024); } while (0)
; #define PG8_LDB(dst, b, h) do { _Pragma("unroll") for (int n = 0; n < 2; ++n) _Pragma("unroll") for (int k = 0; k < 2; ++k) dst[n][k] = *(const PG8_LAS bf16x8*)(lds + PG8_SB(b, h) + boff + n * 2048 + k * 1024); } while (0)
; #define PG8_WAIT_V(n) asm volatile("s_waitcnt vmcnt(" #n ")" ::: "memory")
; #define PG8_WAIT_L(n) asm volatile("s_waitcnt lgkmcnt(" #n ")" ::: "memory")
; #define PG8_BAR __builtin_amdgcn_s_barrier()
; #define PG8_SCHED __builtin_amdgcn_sched_barrier(0)
; template <class Epi, class Sched>
; __device__ __forceinline__ void gemm_phase(PG8_LAS unsigned char* lds, const Gemm g, const Sched& S, const Epi& E) {
;     ...
;     for (;;) {
;         const bool has_next = S.next(ui + 1, nxt);
;         const char* nA = has_next ? (const char*)g.A + (size_t)nxt.pm * tstep : cA; const char* nB = has_next ? (const char*)g.Bt + (size_t)nxt.pn * tstep : cB;
;         for (int t = 0; t < nt; t += 2) {
;             const bool last = (t == nt - 2);
;             const char* a1 = cA + (size_t)(t + 1) * kstep;
;             const char* a2 = last ? nA : cA + (size_t)(t + 2) * kstep; const char* b2 = last ? nB : cB + (size_t)(t + 2) * kstep;
;             const char* a3 = a2 + kstep; const char* b3 = b2 + kstep;
;             PG8_LDB(B0, 0, 0); PG8_SCHED; PG8_LDA(At, 0, 0); PG8_STAGE(PG8_SA(1, 1), a1 + hstep, voffA);
;             PG8_WAIT_L(8); PG8_BAR; PG8_WAIT_L(0); PG8_MMA(0, 0, At, B0); PG8_BAR; PG8_SCHED;
;             PG8_LDB(B1, 0, 1); PG8_STAGE(PG8_SB(0, 0), b2, voffB);
;             PG8_BAR; PG8_WAIT_L(0); PG8_MMA(0, 1, At, B1); PG8_BAR;
;             PG8_LDA(At, 0, 1); PG8_STAGE(PG8_SA(0, 0), a2, voffA);
;             PG8_BAR; PG8_WAIT_L(0); PG8_MMA(1, 0, At, B0); PG8_BAR; PG8_SCHED;
;             PG8_STAGE(PG8_SB(0, 1), b2 + hstep, voffB);
;             PG8_WAIT_V(6); PG8_BAR; PG8_MMA(1, 1, At, B1); PG8_BAR;
.LBB0_694:
	ds_read_b128 v[138:141], v157
	ds_read_b128 v[142:145], v158
	ds_read_b128 v[174:177], v159
	ds_read_b128 v[178:181], v160
	s_add_u32 s30, s28, 0xfffe0080
	s_addc_u32 s31, s29, -1
	s_cmp_eq_u32 s63, 4
	s_cselect_b32 s35, s17, s31
	s_cselect_b32 s34, s59, s30
	s_cselect_b32 s31, s15, s62
	s_cselect_b32 s30, s60, s61
	s_mov_b32 m0, s57
	v_lshl_add_u64 v[214:215], s[28:29], 0, v[134:135]
	ds_read_b128 v[182:185], v155
	ds_read_b128 v[186:189], v155 offset:1024
	ds_read_b128 v[190:193], v155 offset:2048
	ds_read_b128 v[194:197], v155 offset:3072
	ds_read_b128 v[198:201], v155 offset:4096
	ds_read_b128 v[202:205], v155 offset:5120
	ds_read_b128 v[206:209], v155 offset:6144
	ds_read_b128 v[210:213], v155 offset:7168
	global_load_lds_dwordx4 v[214:215], off
	v_lshl_add_u64 v[214:215], s[28:29], 0, v[136:137]
	s_mov_b32 m0, s58
	s_nop 0
	global_load_lds_dwordx4 v[214:215], off
	s_waitcnt lgkmcnt(8)
	s_barrier
	s_waitcnt lgkmcnt(0)
	s_setprio 1
	s_waitcnt lgkmcnt(0)
	v_mfma_f32_16x16x32_bf16 v[126:129], v[138:141], v[182:185], v[126:129]
	v_mfma_f32_16x16x32_bf16 v[122:125], v[174:177], v[182:185], v[122:125]
	v_mfma_f32_16x16x32_bf16 v[118:121], v[138:141], v[190:193], v[118:121]
	v_mfma_f32_16x16x32_bf16 v[106:109], v[174:177], v[190:193], v[106:109]
	v_mfma_f32_16x16x32_bf16 v[98:101], v[138:141], v[198:201], v[98:101]
	v_mfma_f32_16x16x32_bf16 v[94:97], v[174:177], v[198:201], v[94:97]
	v_mfma_f32_16x16x32_bf16 v[86:89], v[138:141], v[206:209], v[86:89]
	v_mfma_f32_16x16x32_bf16 v[78:81], v[174:177], v[206:209], v[78:81]
	v_mfma_f32_16x16x32_bf16 v[126:129], v[142:145], v[186:189], v[126:129]
	v_mfma_f32_16x16x32_bf16 v[122:125], v[178:181], v[186:189], v[122:125]
	v_mfma_f32_16x16x32_bf16 v[118:121], v[142:145], v[194:197], v[118:121]
	v_mfma_f32_16x16x32_bf16 v[106:109], v[178:181], v[194:197], v[106:109]
	v_mfma_f32_16x16x32_bf16 v[98:101], v[142:145], v[202:205], v[98:101]
	v_mfma_f32_16x16x32_bf16 v[94:97], v[178:181], v[202:205], v[94:97]
	v_mfma_f32_16x16x32_bf16 v[86:89], v[142:145], v[210:213], v[86:89]
	v_mfma_f32_16x16x32_bf16 v[78:81], v[178:181], v[210:213], v[78:81]
	s_setprio 0
	s_barrier
	s_mov_b32 m0, s25
	v_lshl_add_u64 v[230:231], s[30:31], 0, v[130:131]
	ds_read_b128 v[214:217], v161
	ds_read_b128 v[218:221], v162
	ds_read_b128 v[222:225], v163
	ds_read_b128 v[226:229], v164
	global_load_lds_dwordx4 v[230:231], off
	v_lshl_add_u64 v[232:233], s[30:31], 0, v[132:133]
	s_mov_b32 m0, s27
	s_nop 0
	global_load_lds_dwordx4 v[232:233], off
	s_barrier
	s_waitcnt lgkmcnt(0)
	s_setprio 1
	s_waitcnt lgkmcnt(0)
	v_mfma_f32_16x16x32_bf16 v[114:117], v[214:217], v[182:185], v[114:117]
	v_mfma_f32_16x16x32_bf16 v[110:113], v[222:225], v[182:185], v[110:113]
	v_mfma_f32_16x16x32_bf16 v[102:105], v[214:217], v[190:193], v[102:105]
	v_mfma_f32_16x16x32_bf16 v[90:93], v[222:225], v[190:193], v[90:93]
	v_mfma_f32_16x16x32_bf16 v[82:85], v[214:217], v[198:201], v[82:85]
	v_mfma_f32_16x16x32_bf16 v[70:73], v[222:225], v[198:201], v[70:73]
	v_mfma_f32_16x16x32_bf16 v[74:77], v[214:217], v[206:209], v[74:77]
	v_mfma_f32_16x16x32_bf16 v[66:69], v[222:225], v[206:209], v[66:69]
	v_mfma_f32_16x16x32_bf16 v[114:117], v[218:221], v[186:189], v[114:117]
	v_mfma_f32_16x16x32_bf16 v[110:113], v[226:229], v[186:189], v[110:113]
	v_mfma_f32_16x16x32_bf16 v[102:105], v[218:221], v[194:197], v[102:105]
	v_mfma_f32_16x16x32_bf16 v[90:93], v[226:229], v[194:197], v[90:93]
	v_mfma_f32_16x16x32_bf16 v[82:85], v[218:221], v[202:205], v[82:85]
	v_mfma_f32_16x16x32_bf16 v[70:73], v[226:229], v[202:205], v[70:73]
	v_mfma_f32_16x16x32_bf16 v[74:77], v[218:221], v[210:213], v[74:77]
	v_mfma_f32_16x16x32_bf16 v[66:69], v[226:229], v[210:213], v[66:69]
	s_setprio 0
	s_mov_b32 m0, s40
	v_lshl_add_u64 v[234:235], s[34:35], 0, v[130:131]
	s_barrier
	ds_read_b128 v[182:185], v155 offset:16384
	ds_read_b128 v[186:189], v155 offset:17408
	ds_read_b128 v[190:193], v155 offset:18432
	ds_read_b128 v[194:197], v155 offset:19456
	ds_read_b128 v[198:201], v155 offset:20480
	ds_read_b128 v[202:205], v155 offset:21504
	ds_read_b128 v[206:209], v155 offset:22528
	ds_read_b128 v[210:213], v155 offset:23552
	global_load_lds_dwordx4 v[234:235], off
	v_lshl_add_u64 v[236:237], s[34:35], 0, v[132:133]
	s_mov_b32 m0, s41
	s_nop 0
	global_load_lds_dwordx4 v[236:237], off
	s_barrier
	s_waitcnt lgkmcnt(0)
	s_setprio 1
	s_waitcnt lgkmcnt(0)
	v_mfma_f32_16x16x32_bf16 v[62:65], v[138:141], v[182:185], v[62:65]
	v_mfma_f32_16x16x32_bf16 v[58:61], v[174:177], v[182:185], v[58:61]
	v_mfma_f32_16x16x32_bf16 v[50:53], v[138:141], v[190:193], v[50:53]
	v_mfma_f32_16x16x32_bf16 v[42:45], v[174:177], v[190:193], v[42:45]
	v_mfma_f32_16x16x32_bf16 v[30:33], v[138:141], v[198:201], v[30:33]
	v_mfma_f32_16x16x32_bf16 v[26:29], v[174:177], v[198:201], v[26:29]
	v_mfma_f32_16x16x32_bf16 v[14:17], v[138:141], v[206:209], v[14:17]
	v_mfma_f32_16x16x32_bf16 v[10:13], v[174:177], v[206:209], v[10:13]
	v_mfma_f32_16x16x32_bf16 v[62:65], v[142:145], v[186:189], v[62:65]
	v_mfma_f32_16x16x32_bf16 v[58:61], v[178:181], v[186:189], v[58:61]
	v_mfma_f32_16x16x32_bf16 v[50:53], v[142:145], v[194:197], v[50:53]
	v_mfma_f32_16x16x32_bf16 v[42:45], v[178:181], v[194:197], v[42:45]
	v_mfma_f32_16x16x32_bf16 v[30:33], v[142:145], v[202:205], v[30:33]
	v_mfma_f32_16x16x32_bf16 v[26:29], v[178:181], v[202:205], v[26:29]
	v_mfma_f32_16x16x32_bf16 v[14:17], v[142:145], v[210:213], v[14:17]
	v_mfma_f32_16x16x32_bf16 v[10:13], v[178:181], v[210:213], v[10:13]
	s_setprio 0
	s_barrier
; #define PG8_STAGE(bufoff, gbase, voff) do { _Pragma("unroll") for (int _i = 0; _i < 2; ++_i) \
;         __builtin_amdgcn_global_load_lds((const unsigned*)((const char*)(gbase) + (voff)[_i]), (PG8_LAS unsigned*)(lds + (bufoff) + ldsw + _i * 8192), 16, 0, 0); } while (0)
; #define PG8_LDA(dst, b, h) do { _Pragma("unroll") for (int m = 0; m < 4; ++m) _Pragma("unroll") for (int k = 0; k < 2; ++k) dst[m][k] = *(const PG8_LAS bf16x8*)(lds + PG8_SA(b, h) + aoff + m * 2048 + k * 1024); } while (0)
; #define PG8_LDB(dst, b, h) do { _Pragma("unroll") for (int n = 0; n < 2; ++n) _Pragma("unroll") for (int k = 0; k < 2; ++k) dst[n][k] = *(const PG8_LAS bf16x8*)(lds + PG8_SB(b, h) + boff + n * 2048 + k * 1024); } while (0)
; #define PG8_MMA(ai, bj, At, Bt) do { __builtin_amdgcn_s_setprio(1); _Pragma("unroll") for (int m = 0; m < 4; ++m) _Pragma("unroll") for (int n = 0; n < 2; ++n) _Pragma("unroll") for (int k = 0; k < 2; ++k) \
;         acc[ai][bj][m][n] = __builtin_amdgcn_mfma_f32_16x16x32_bf16(Bt[n][k], At[m][k], acc[ai][bj][m][n], 0, 0, 0); __builtin_amdgcn_s_setprio(0); } while (0)
; #define PG8_WAIT_V(n) asm volatile("s_waitcnt vmcnt(" #n ")" ::: "memory")
; #define PG8_WAIT_L(n) asm volatile("s_waitcnt lgkmcnt(" #n ")" ::: "memory")
; #define PG8_BAR __builtin_amdgcn_s_barrier()
; #define PG8_SCHED __builtin_amdgcn_sched_barrier(0)
; template <class Epi, class Sched>
; __device__ __forceinline__ void gemm_phase(PG8_LAS unsigned char* lds, const Gemm g, const Sched& S, const Epi& E) {
;     ...
;             PG8_WAIT_V(6); PG8_BAR; PG8_MMA(1, 1, At, B1); PG8_BAR;
;             PG8_LDB(B0, 1, 0); PG8_SCHED; PG8_LDA(At, 1, 0); PG8_STAGE(PG8_SA(0, 1), a2 + hstep, voffA);
;             PG8_WAIT_L(8); PG8_BAR; PG8_WAIT_L(0); PG8_MMA(0, 0, At, B0); PG8_BAR; PG8_SCHED;
;             PG8_LDB(B1, 1, 1); PG8_STAGE(PG8_SB(1, 0), b3, voffB);
;             PG8_BAR; PG8_WAIT_L(0); PG8_MMA(0, 1, At, B1); PG8_BAR;
;             PG8_LDA(At, 1, 1); PG8_STAGE(PG8_SA(1, 0), a3, voffA);
;             PG8_BAR; PG8_WAIT_L(0); PG8_MMA(1, 0, At, B0); PG8_BAR; PG8_SCHED;
;             PG8_STAGE(PG8_SB(1, 1), b3 + hstep, voffB);
;             PG8_WAIT_V(6); PG8_BAR; PG8_MMA(1, 1, At, B1); PG8_BAR;
	s_add_u32 s64, s30, 0x20000
	s_addc_u32 s65, s31, 0
	s_mov_b32 m0, s42
	v_lshl_add_u64 v[138:139], s[64:65], 0, v[130:131]
	global_load_lds_dwordx4 v[138:139], off
	v_lshl_add_u64 v[138:139], s[64:65], 0, v[132:133]
	s_mov_b32 m0, s43
	s_nop 0
	global_load_lds_dwordx4 v[138:139], off
	s_waitcnt vmcnt(6)
	s_barrier
	s_setprio 1
	v_mfma_f32_16x16x32_bf16 v[54:57], v[214:217], v[182:185], v[54:57]
	v_mfma_f32_16x16x32_bf16 v[46:49], v[222:225], v[182:185], v[46:49]
	v_mfma_f32_16x16x32_bf16 v[38:41], v[214:217], v[190:193], v[38:41]
	v_mfma_f32_16x16x32_bf16 v[34:37], v[222:225], v[190:193], v[34:37]
	v_mfma_f32_16x16x32_bf16 v[22:25], v[214:217], v[198:201], v[22:25]
	v_mfma_f32_16x16x32_bf16 v[18:21], v[222:225], v[198:201], v[18:21]
	v_mfma_f32_16x16x32_bf16 v[6:9], v[214:217], v[206:209], v[6:9]
	v_mfma_f32_16x16x32_bf16 v[2:5], v[222:225], v[206:209], v[2:5]
	v_mfma_f32_16x16x32_bf16 v[54:57], v[218:221], v[186:189], v[54:57]
	v_mfma_f32_16x16x32_bf16 v[46:49], v[226:229], v[186:189], v[46:49]
	v_mfma_f32_16x16x32_bf16 v[38:41], v[218:221], v[194:197], v[38:41]
	v_mfma_f32_16x16x32_bf16 v[34:37], v[226:229], v[194:197], v[34:37]
	v_mfma_f32_16x16x32_bf16 v[22:25], v[218:221], v[202:205], v[22:25]
	v_mfma_f32_16x16x32_bf16 v[18:21], v[226:229], v[202:205], v[18:21]
	v_mfma_f32_16x16x32_bf16 v[6:9], v[218:221], v[210:213], v[6:9]
	v_mfma_f32_16x16x32_bf16 v[2:5], v[226:229], v[210:213], v[2:5]
	s_setprio 0
	s_barrier
	ds_read_b128 v[138:141], v165
	ds_read_b128 v[142:145], v166
	ds_read_b128 v[174:177], v167
	ds_read_b128 v[178:181], v168
	s_add_u32 s34, s34, 0x20000
	s_addc_u32 s35, s35, 0
	s_mov_b32 m0, s44
	v_lshl_add_u64 v[214:215], s[34:35], 0, v[130:131]
	ds_read_b128 v[182:185], v155 offset:32768
	ds_read_b128 v[186:189], v155 offset:33792
	ds_read_b128 v[190:193], v155 offset:34816
	ds_read_b128 v[194:197], v155 offset:35840
	ds_read_b128 v[198:201], v155 offset:36864
	ds_read_b128 v[202:205], v155 offset:37888
	ds_read_b128 v[206:209], v155 offset:38912
	ds_read_b128 v[210:213], v155 offset:39936
	global_load_lds_dwordx4 v[214:215], off
	v_lshl_add_u64 v[214:215], s[34:35], 0, v[132:133]
	s_mov_b32 m0, s45
	s_nop 0
	global_load_lds_dwordx4 v[214:215], off
	s_waitcnt lgkmcnt(8)
	s_barrier
	s_waitcnt lgkmcnt(0)
	s_setprio 1
	s_waitcnt lgkmcnt(0)
	v_mfma_f32_16x16x32_bf16 v[126:129], v[138:141], v[182:185], v[126:129]
	v_mfma_f32_16x16x32_bf16 v[122:125], v[174:177], v[182:185], v[122:125]
	v_mfma_f32_16x16x32_bf16 v[118:121], v[138:141], v[190:193], v[118:121]
	v_mfma_f32_16x16x32_bf16 v[106:109], v[174:177], v[190:193], v[106:109]
	v_mfma_f32_16x16x32_bf16 v[98:101], v[138:141], v[198:201], v[98:101]
	v_mfma_f32_16x16x32_bf16 v[94:97], v[174:177], v[198:201], v[94:97]
	v_mfma_f32_16x16x32_bf16 v[86:89], v[138:141], v[206:209], v[86:89]
	v_mfma_f32_16x16x32_bf16 v[78:81], v[174:177], v[206:209], v[78:81]
	v_mfma_f32_16x16x32_bf16 v[126:129], v[142:145], v[186:189], v[126:129]
	v_mfma_f32_16x16x32_bf16 v[122:125], v[178:181], v[186:189], v[122:125]
	v_mfma_f32_16x16x32_bf16 v[118:121], v[142:145], v[194:197], v[118:121]
	v_mfma_f32_16x16x32_bf16 v[106:109], v[178:181], v[194:197], v[106:109]
	v_mfma_f32_16x16x32_bf16 v[98:101], v[142:145], v[202:205], v[98:101]
	v_mfma_f32_16x16x32_bf16 v[94:97], v[178:181], v[202:205], v[94:97]
	v_mfma_f32_16x16x32_bf16 v[86:89], v[142:145], v[210:213], v[86:89]
	v_mfma_f32_16x16x32_bf16 v[78:81], v[178:181], v[210:213], v[78:81]
	s_setprio 0
	s_barrier
	s_mov_b32 m0, s46
	v_lshl_add_u64 v[230:231], v[230:231], 0, s[8:9]
	ds_read_b128 v[214:217], v169
	ds_read_b128 v[218:221], v170
	ds_read_b128 v[222:225], v171
	ds_read_b128 v[226:229], v172
	global_load_lds_dwordx4 v[230:231], off
	v_lshl_add_u64 v[230:231], v[232:233], 0, s[8:9]
	s_mov_b32 m0, s47
	s_nop 0
	global_load_lds_dwordx4 v[230:231], off
	s_barrier
	s_waitcnt lgkmcnt(0)
	s_setprio 1
	s_waitcnt lgkmcnt(0)
	v_mfma_f32_16x16x32_bf16 v[114:117], v[214:217], v[182:185], v[114:117]
	v_mfma_f32_16x16x32_bf16 v[110:113], v[222:225], v[182:185], v[110:113]
	v_mfma_f32_16x16x32_bf16 v[102:105], v[214:217], v[190:193], v[102:105]
	v_mfma_f32_16x16x32_bf16 v[90:93], v[222:225], v[190:193], v[90:93]
	v_mfma_f32_16x16x32_bf16 v[82:85], v[214:217], v[198:201], v[82:85]
	v_mfma_f32_16x16x32_bf16 v[70:73], v[222:225], v[198:201], v[70:73]
	v_mfma_f32_16x16x32_bf16 v[74:77], v[214:217], v[206:209], v[74:77]
	v_mfma_f32_16x16x32_bf16 v[66:69], v[222:225], v[206:209], v[66:69]
	v_mfma_f32_16x16x32_bf16 v[114:117], v[218:221], v[186:189], v[114:117]
	v_mfma_f32_16x16x32_bf16 v[110:113], v[226:229], v[186:189], v[110:113]
	v_mfma_f32_16x16x32_bf16 v[102:105], v[218:221], v[194:197], v[102:105]
	v_mfma_f32_16x16x32_bf16 v[90:93], v[226:229], v[194:197], v[90:93]
	v_mfma_f32_16x16x32_bf16 v[82:85], v[218:221], v[202:205], v[82:85]
	v_mfma_f32_16x16x32_bf16 v[70:73], v[226:229], v[202:205], v[70:73]
	v_mfma_f32_16x16x32_bf16 v[74:77], v[218:221], v[210:213], v[74:77]
	v_mfma_f32_16x16x32_bf16 v[66:69], v[226:229], v[210:213], v[66:69]
	s_setprio 0
	s_mov_b32 m0, s48
	v_lshl_add_u64 v[230:231], v[234:235], 0, s[8:9]
	s_barrier
	ds_read_b128 v[182:185], v155 offset:49152
	ds_read_b128 v[186:189], v155 offset:50176
	ds_read_b128 v[190:193], v155 offset:51200
	ds_read_b128 v[194:197], v155 offset:52224
	ds_read_b128 v[198:201], v155 offset:53248
	ds_read_b128 v[202:205], v155 offset:54272
	ds_read_b128 v[206:209], v155 offset:55296
	ds_read_b128 v[210:213], v155 offset:56320
	global_load_lds_dwordx4 v[230:231], off
	v_lshl_add_u64 v[230:231], v[236:237], 0, s[8:9]
	s_mov_b32 m0, s49
	s_nop 0
	global_load_lds_dwordx4 v[230:231], off
	s_barrier
; __device__ __forceinline__ float bflo(uint32_t v) { return __uint_as_float(v << 16); }
; __device__ __forceinline__ float bfhi(uint32_t v) { return __uint_as_float(v & 0xFFFF0000u); }
; template <class Epi, class Sched>
; __device__ __forceinline__ void gemm_phase(PG8_LAS unsigned char* lds, const Gemm g, const Sched& S, const Epi& E) {
;     ...
;         E(acc, cur, wr, wc, fr, fq);
;   __device__ __forceinline__ void operator()(const acc8_t& acc, const pg8::Unit& u, int wr, int wc, int fr, int fq) const {
;     const u16* GA = (const u16*)(ws + OFF_GA); u16* M = (u16*)(ws + OFF_M);
; #pragma unroll
;     for (int ai = 0; ai < 2; ai++)
; #pragma unroll
;       for (int m = 0; m < 4; m++) {
;         const size_t token = EPI_TOKEN(u, ai, m);
; #pragma unroll
;         for (int bj = 0; bj < 2; bj++)
; #pragma unroll
;           for (int n = 0; n < 2; n++) {
;             const int f = EPI_COL(u, bj, n);
;             const uint2 ga = *(const uint2*)(GA + token * 1024 + f);
;             uint2 o;
;             o.x = pack2(bflo(ga.x) * acc[ai][bj][m][n][0], bfhi(ga.x) * acc[ai][bj][m][n][1]);
;             o.y = pack2(bflo(ga.y) * acc[ai][bj][m][n][2], bfhi(ga.y) * acc[ai][bj][m][n][3]);
;             *(uint2*)(M + token * 1024 + f) = o;
;           }
;       }
	s_waitcnt lgkmcnt(0)
	s_setprio 1
	s_waitcnt lgkmcnt(0)
	v_mfma_f32_16x16x32_bf16 v[62:65], v[138:141], v[182:185], v[62:65]
	v_mfma_f32_16x16x32_bf16 v[58:61], v[174:177], v[182:185], v[58:61]
	v_mfma_f32_16x16x32_bf16 v[50:53], v[138:141], v[190:193], v[50:53]
	v_mfma_f32_16x16x32_bf16 v[42:45], v[174:177], v[190:193], v[42:45]
	v_mfma_f32_16x16x32_bf16 v[30:33], v[138:141], v[198:201], v[30:33]
	v_mfma_f32_16x16x32_bf16 v[26:29], v[174:177], v[198:201], v[26:29]
	v_mfma_f32_16x16x32_bf16 v[14:17], v[138:141], v[206:209], v[14:17]
	v_mfma_f32_16x16x32_bf16 v[10:13], v[174:177], v[206:209], v[10:13]
	v_mfma_f32_16x16x32_bf16 v[62:65], v[142:145], v[186:189], v[62:65]
	v_mfma_f32_16x16x32_bf16 v[58:61], v[178:181], v[186:189], v[58:61]
	v_mfma_f32_16x16x32_bf16 v[50:53], v[142:145], v[194:197], v[50:53]
	v_mfma_f32_16x16x32_bf16 v[42:45], v[178:181], v[194:197], v[42:45]
	v_mfma_f32_16x16x32_bf16 v[30:33], v[142:145], v[202:205], v[30:33]
	v_mfma_f32_16x16x32_bf16 v[26:29], v[178:181], v[202:205], v[26:29]
	v_mfma_f32_16x16x32_bf16 v[14:17], v[142:145], v[210:213], v[14:17]
	v_mfma_f32_16x16x32_bf16 v[10:13], v[178:181], v[210:213], v[10:13]
	s_setprio 0
	s_barrier
	s_add_u32 s30, s30, 0x20080
	s_addc_u32 s31, s31, 0
	s_mov_b32 m0, s50
	v_lshl_add_u64 v[138:139], s[30:31], 0, v[130:131]
	global_load_lds_dwordx4 v[138:139], off
	v_lshl_add_u64 v[138:139], s[30:31], 0, v[132:133]
	s_mov_b32 m0, s51
	s_nop 0
	global_load_lds_dwordx4 v[138:139], off
	s_waitcnt vmcnt(6)
	s_barrier
	s_setprio 1
	v_mfma_f32_16x16x32_bf16 v[54:57], v[214:217], v[182:185], v[54:57]
	v_mfma_f32_16x16x32_bf16 v[46:49], v[222:225], v[182:185], v[46:49]
	v_mfma_f32_16x16x32_bf16 v[38:41], v[214:217], v[190:193], v[38:41]
	v_mfma_f32_16x16x32_bf16 v[34:37], v[222:225], v[190:193], v[34:37]
	v_mfma_f32_16x16x32_bf16 v[22:25], v[214:217], v[198:201], v[22:25]
	v_mfma_f32_16x16x32_bf16 v[18:21], v[222:225], v[198:201], v[18:21]
	v_mfma_f32_16x16x32_bf16 v[6:9], v[214:217], v[206:209], v[6:9]
	v_mfma_f32_16x16x32_bf16 v[2:5], v[222:225], v[206:209], v[2:5]
	v_mfma_f32_16x16x32_bf16 v[54:57], v[218:221], v[186:189], v[54:57]
	v_mfma_f32_16x16x32_bf16 v[46:49], v[226:229], v[186:189], v[46:49]
	v_mfma_f32_16x16x32_bf16 v[38:41], v[218:221], v[194:197], v[38:41]
	v_mfma_f32_16x16x32_bf16 v[34:37], v[226:229], v[194:197], v[34:37]
	v_mfma_f32_16x16x32_bf16 v[22:25], v[218:221], v[202:205], v[22:25]
	v_mfma_f32_16x16x32_bf16 v[18:21], v[226:229], v[202:205], v[18:21]
	v_mfma_f32_16x16x32_bf16 v[6:9], v[218:221], v[210:213], v[6:9]
	v_mfma_f32_16x16x32_bf16 v[2:5], v[226:229], v[210:213], v[2:5]
	s_setprio 0
	s_add_i32 s63, s63, 2
	s_add_u32 s28, s28, 0x100
	s_addc_u32 s29, s29, 0
	s_add_u32 s61, s61, 0x100
	s_addc_u32 s62, s62, 0
	s_cmp_gt_u32 s63, 5
	s_barrier
	s_cbranch_scc0 .LBB0_694
	v_lshl_add_u32 v138, s26, 8, v154
	v_lshl_or_b32 v140, s24, 8, v156
	v_ashrrev_i32_e32 v139, 31, v138
	v_ashrrev_i32_e32 v141, 31, v140
	v_lshlrev_b64 v[142:143], 11, v[138:139]
	v_lshlrev_b64 v[140:141], 1, v[140:141]
	v_bfe_u32 v144, v0, 4, 1
	v_mov_b32_e32 v145, 0
	v_mul_u32_u24_e32 v144, 24, v144
	v_lshl_add_u64 v[142:143], v[142:143], 0, v[140:141]
	v_lshl_add_u64 v[142:143], v[142:143], 0, v[144:145]
	v_lshl_add_u64 v[230:231], s[10:11], 0, v[142:143]
	v_lshl_add_u64 v[234:235], s[12:13], 0, v[142:143]
	s_mov_b32 s24, s14
	s_mov_b32 s26, s16
	s_mov_b64 s[30:31], s[22:23]
	s_mov_b64 s[28:29], s[20:21]
	global_load_dwordx4 v[174:177], v[230:231], off
	global_load_dwordx4 v[178:181], v[230:231], off offset:256
	s_mov_b64 s[4:5], 0x8000
	v_lshl_add_u64 v[230:231], v[230:231], 0, s[4:5]
	global_load_dwordx4 v[190:193], v[230:231], off
	global_load_dwordx4 v[194:197], v[230:231], off offset:256
	v_permlane16_swap_b32_e32 v126, v122
	v_permlane16_swap_b32_e32 v127, v123
	v_permlane16_swap_b32_e32 v128, v124
	v_permlane16_swap_b32_e32 v129, v125
	v_permlane16_swap_b32_e32 v114, v110
	v_permlane16_swap_b32_e32 v115, v111
	v_permlane16_swap_b32_e32 v116, v112
	v_permlane16_swap_b32_e32 v117, v113
	s_mov_b64 s[4:5], 0x8000
	v_lshl_add_u64 v[230:231], v[230:231], 0, s[4:5]
	global_load_dwordx4 v[206:209], v[230:231], off
	global_load_dwordx4 v[210:213], v[230:231], off offset:256
	s_waitcnt vmcnt(4)
	v_lshlrev_b32_e32 v222, 16, v174
	v_and_b32_e32 v223, 0xffff0000, v174
	v_pk_mul_f32 v[126:127], v[126:127], v[222:223]
	v_lshlrev_b32_e32 v224, 16, v175
	v_and_b32_e32 v225, 0xffff0000, v175
	v_pk_mul_f32 v[128:129], v[128:129], v[224:225]
	v_lshlrev_b32_e32 v226, 16, v176
	v_and_b32_e32 v227, 0xffff0000, v176
	v_pk_mul_f32 v[122:123], v[122:123], v[226:227]
	v_lshlrev_b32_e32 v228, 16, v177
	v_and_b32_e32 v229, 0xffff0000, v177
	v_pk_mul_f32 v[124:125], v[124:125], v[228:229]
	v_cvt_pk_bf16_f32 v138, v126, v127
	v_cvt_pk_bf16_f32 v139, v128, v129
	v_cvt_pk_bf16_f32 v140, v122, v123
	v_cvt_pk_bf16_f32 v141, v124, v125
	v_lshlrev_b32_e32 v222, 16, v178
	v_and_b32_e32 v223, 0xffff0000, v178
	v_pk_mul_f32 v[114:115], v[114:115], v[222:223]
	v_lshlrev_b32_e32 v224, 16, v179
	v_and_b32_e32 v225, 0xffff0000, v179
	v_pk_mul_f32 v[116:117], v[116:117], v[224:225]
	v_lshlrev_b32_e32 v226, 16, v180
	v_and_b32_e32 v227, 0xffff0000, v180
	v_pk_mul_f32 v[110:111], v[110:111], v[226:227]
	v_lshlrev_b32_e32 v228, 16, v181
	v_and_b32_e32 v229, 0xffff0000, v181
	v_pk_mul_f32 v[112:113], v[112:113], v[228:229]
	v_cvt_pk_bf16_f32 v142, v114, v115
	v_cvt_pk_bf16_f32 v143, v116, v117
	v_cvt_pk_bf16_f32 v144, v110, v111
	v_cvt_pk_bf16_f32 v145, v112, v113
	global_store_dwordx4 v[234:235], v[138:141], off
	global_store_dwordx4 v[234:235], v[142:145], off offset:256
	s_mov_b64 s[4:5], 0x8000
	v_lshl_add_u64 v[234:235], v[234:235], 0, s[4:5]
	v_permlane16_swap_b32_e32 v118, v106
	v_permlane16_swap_b32_e32 v119, v107
	v_permlane16_swap_b32_e32 v120, v108
	v_permlane16_swap_b32_e32 v121, v109
	v_permlane16_swap_b32_e32 v102, v90
	v_permlane16_swap_b32_e32 v103, v91
	v_permlane16_swap_b32_e32 v104, v92
	v_permlane16_swap_b32_e32 v105, v93
	s_mov_b64 s[4:5], 0x8000
	v_lshl_add_u64 v[230:231], v[230:231], 0, s[4:5]
	global_load_dwordx4 v[174:177], v[230:231], off
	global_load_dwordx4 v[178:181], v[230:231], off offset:256
	s_waitcnt vmcnt(6)
; __device__ __forceinline__ float bflo(uint32_t v) { return __uint_as_float(v << 16); }
; __device__ __forceinline__ float bfhi(uint32_t v) { return __uint_as_float(v & 0xFFFF0000u); }
;   __device__ __forceinline__ void operator()(const acc8_t& acc, const pg8::Unit& u, int wr, int wc, int fr, int fq) const {
;     const u16* GA = (const u16*)(ws + OFF_GA); u16* M = (u16*)(ws + OFF_M);
; #pragma unroll
;     for (int ai = 0; ai < 2; ai++)
; #pragma unroll
;       for (int m = 0; m < 4; m++) {
;         const size_t token = EPI_TOKEN(u, ai, m);
; #pragma unroll
;         for (int bj = 0; bj < 2; bj++)
; #pragma unroll
;           for (int n = 0; n < 2; n++) {
;             const int f = EPI_COL(u, bj, n);
;             const uint2 ga = *(const uint2*)(GA + token * 1024 + f);
;             uint2 o;
;             o.x = pack2(bflo(ga.x) * acc[ai][bj][m][n][0], bfhi(ga.x) * acc[ai][bj][m][n][1]);
;             o.y = pack2(bflo(ga.y) * acc[ai][bj][m][n][2], bfhi(ga.y) * acc[ai][bj][m][n][3]);
;             *(uint2*)(M + token * 1024 + f) = o;
;           }
;       }
	v_lshlrev_b32_e32 v222, 16, v190
	v_and_b32_e32 v223, 0xffff0000, v190
	v_pk_mul_f32 v[118:119], v[118:119], v[222:223]
	v_lshlrev_b32_e32 v224, 16, v191
	v_and_b32_e32 v225, 0xffff0000, v191
	v_pk_mul_f32 v[120:121], v[120:121], v[224:225]
	v_lshlrev_b32_e32 v226, 16, v192
	v_and_b32_e32 v227, 0xffff0000, v192
	v_pk_mul_f32 v[106:107], v[106:107], v[226:227]
	v_lshlrev_b32_e32 v228, 16, v193
	v_and_b32_e32 v229, 0xffff0000, v193
	v_pk_mul_f32 v[108:109], v[108:109], v[228:229]
	v_cvt_pk_bf16_f32 v138, v118, v119
	v_cvt_pk_bf16_f32 v139, v120, v121
	v_cvt_pk_bf16_f32 v140, v106, v107
	v_cvt_pk_bf16_f32 v141, v108, v109
	v_lshlrev_b32_e32 v222, 16, v194
	v_and_b32_e32 v223, 0xffff0000, v194
	v_pk_mul_f32 v[102:103], v[102:103], v[222:223]
	v_lshlrev_b32_e32 v224, 16, v195
	v_and_b32_e32 v225, 0xffff0000, v195
	v_pk_mul_f32 v[104:105], v[104:105], v[224:225]
	v_lshlrev_b32_e32 v226, 16, v196
	v_and_b32_e32 v227, 0xffff0000, v196
	v_pk_mul_f32 v[90:91], v[90:91], v[226:227]
	v_lshlrev_b32_e32 v228, 16, v197
	v_and_b32_e32 v229, 0xffff0000, v197
	v_pk_mul_f32 v[92:93], v[92:93], v[228:229]
	v_cvt_pk_bf16_f32 v142, v102, v103
	v_cvt_pk_bf16_f32 v143, v104, v105
	v_cvt_pk_bf16_f32 v144, v90, v91
	v_cvt_pk_bf16_f32 v145, v92, v93
	global_store_dwordx4 v[234:235], v[138:141], off
	global_store_dwordx4 v[234:235], v[142:145], off offset:256
	s_mov_b64 s[4:5], 0x8000
	v_lshl_add_u64 v[234:235], v[234:235], 0, s[4:5]
	v_permlane16_swap_b32_e32 v98, v94
	v_permlane16_swap_b32_e32 v99, v95
	v_permlane16_swap_b32_e32 v100, v96
	v_permlane16_swap_b32_e32 v101, v97
	v_permlane16_swap_b32_e32 v82, v70
	v_permlane16_swap_b32_e32 v83, v71
	v_permlane16_swap_b32_e32 v84, v72
	v_permlane16_swap_b32_e32 v85, v73
	s_mov_b64 s[4:5], 0x28000
	v_lshl_add_u64 v[230:231], v[230:231], 0, s[4:5]
	global_load_dwordx4 v[190:193], v[230:231], off
	global_load_dwordx4 v[194:197], v[230:231], off offset:256
	s_waitcnt vmcnt(8)
	v_lshlrev_b32_e32 v222, 16, v206
	v_and_b32_e32 v223, 0xffff0000, v206
	v_pk_mul_f32 v[98:99], v[98:99], v[222:223]
	v_lshlrev_b32_e32 v224, 16, v207
	v_and_b32_e32 v225, 0xffff0000, v207
	v_pk_mul_f32 v[100:101], v[100:101], v[224:225]
	v_lshlrev_b32_e32 v226, 16, v208
	v_and_b32_e32 v227, 0xffff0000, v208
	v_pk_mul_f32 v[94:95], v[94:95], v[226:227]
	v_lshlrev_b32_e32 v228, 16, v209
	v_and_b32_e32 v229, 0xffff0000, v209
	v_pk_mul_f32 v[96:97], v[96:97], v[228:229]
	v_cvt_pk_bf16_f32 v138, v98, v99
	v_cvt_pk_bf16_f32 v139, v100, v101
	v_cvt_pk_bf16_f32 v140, v94, v95
	v_cvt_pk_bf16_f32 v141, v96, v97
	v_lshlrev_b32_e32 v222, 16, v210
	v_and_b32_e32 v223, 0xffff0000, v210
	v_pk_mul_f32 v[82:83], v[82:83], v[222:223]
	v_lshlrev_b32_e32 v224, 16, v211
	v_and_b32_e32 v225, 0xffff0000, v211
	v_pk_mul_f32 v[84:85], v[84:85], v[224:225]
	v_lshlrev_b32_e32 v226, 16, v212
	v_and_b32_e32 v227, 0xffff0000, v212
	v_pk_mul_f32 v[70:71], v[70:71], v[226:227]
	v_lshlrev_b32_e32 v228, 16, v213
	v_and_b32_e32 v229, 0xffff0000, v213
	v_pk_mul_f32 v[72:73], v[72:73], v[228:229]
	v_cvt_pk_bf16_f32 v142, v82, v83
	v_cvt_pk_bf16_f32 v143, v84, v85
	v_cvt_pk_bf16_f32 v144, v70, v71
	v_cvt_pk_bf16_f32 v145, v72, v73
	global_store_dwordx4 v[234:235], v[138:141], off
	global_store_dwordx4 v[234:235], v[142:145], off offset:256
	s_mov_b64 s[4:5], 0x8000
	v_lshl_add_u64 v[234:235], v[234:235], 0, s[4:5]
	v_permlane16_swap_b32_e32 v86, v78
	v_permlane16_swap_b32_e32 v87, v79
	v_permlane16_swap_b32_e32 v88, v80
	v_permlane16_swap_b32_e32 v89, v81
	v_permlane16_swap_b32_e32 v74, v66
	v_permlane16_swap_b32_e32 v75, v67
	v_permlane16_swap_b32_e32 v76, v68
	v_permlane16_swap_b32_e32 v77, v69
	s_mov_b64 s[4:5], 0x8000
	v_lshl_add_u64 v[230:231], v[230:231], 0, s[4:5]
	global_load_dwordx4 v[206:209], v[230:231], off
	global_load_dwordx4 v[210:213], v[230:231], off offset:256
	s_waitcnt vmcnt(8)
	v_lshlrev_b32_e32 v222, 16, v174
	v_and_b32_e32 v223, 0xffff0000, v174
	v_pk_mul_f32 v[86:87], v[86:87], v[222:223]
	v_lshlrev_b32_e32 v224, 16, v175
	v_and_b32_e32 v225, 0xffff0000, v175
	v_pk_mul_f32 v[88:89], v[88:89], v[224:225]
	v_lshlrev_b32_e32 v226, 16, v176
	v_and_b32_e32 v227, 0xffff0000, v176
	v_pk_mul_f32 v[78:79], v[78:79], v[226:227]
	v_lshlrev_b32_e32 v228, 16, v177
	v_and_b32_e32 v229, 0xffff0000, v177
	v_pk_mul_f32 v[80:81], v[80:81], v[228:229]
	v_cvt_pk_bf16_f32 v138, v86, v87
	v_cvt_pk_bf16_f32 v139, v88, v89
	v_cvt_pk_bf16_f32 v140, v78, v79
	v_cvt_pk_bf16_f32 v141, v80, v81
	v_lshlrev_b32_e32 v222, 16, v178
	v_and_b32_e32 v223, 0xffff0000, v178
	v_pk_mul_f32 v[74:75], v[74:75], v[222:223]
	v_lshlrev_b32_e32 v224, 16, v179
	v_and_b32_e32 v225, 0xffff0000, v179
	v_pk_mul_f32 v[76:77], v[76:77], v[224:225]
	v_lshlrev_b32_e32 v226, 16, v180
	v_and_b32_e32 v227, 0xffff0000, v180
	v_pk_mul_f32 v[66:67], v[66:67], v[226:227]
	v_lshlrev_b32_e32 v228, 16, v181
	v_and_b32_e32 v229, 0xffff0000, v181
	v_pk_mul_f32 v[68:69], v[68:69], v[228:229]
	v_cvt_pk_bf16_f32 v142, v74, v75
	v_cvt_pk_bf16_f32 v143, v76, v77
	v_cvt_pk_bf16_f32 v144, v66, v67
	v_cvt_pk_bf16_f32 v145, v68, v69
	global_store_dwordx4 v[234:235], v[138:141], off
	global_store_dwordx4 v[234:235], v[142:145], off offset:256
	s_mov_b64 s[4:5], 0x28000
	v_lshl_add_u64 v[234:235], v[234:235], 0, s[4:5]
	v_permlane16_swap_b32_e32 v62, v58
	v_permlane16_swap_b32_e32 v63, v59
	v_permlane16_swap_b32_e32 v64, v60
	v_permlane16_swap_b32_e32 v65, v61
	v_permlane16_swap_b32_e32 v54, v46
	v_permlane16_swap_b32_e32 v55, v47
	v_permlane16_swap_b32_e32 v56, v48
	v_permlane16_swap_b32_e32 v57, v49
	s_mov_b64 s[4:5], 0x8000
	v_lshl_add_u64 v[230:231], v[230:231], 0, s[4:5]
	global_load_dwordx4 v[174:177], v[230:231], off
	global_load_dwordx4 v[178:181], v[230:231], off offset:256
	s_waitcnt vmcnt(8)
; __device__ __forceinline__ float bflo(uint32_t v) { return __uint_as_float(v << 16); }
; __device__ __forceinline__ float bfhi(uint32_t v) { return __uint_as_float(v & 0xFFFF0000u); }
; #define PG8_WAIT_V(n) asm volatile("s_waitcnt vmcnt(" #n ")" ::: "memory")
; #define PG8_BAR __builtin_amdgcn_s_barrier()
; template <class Epi, class Sched>
; __device__ __forceinline__ void gemm_phase(PG8_LAS unsigned char* lds, const Gemm g, const Sched& S, const Epi& E) {
;     ...
;         E(acc, cur, wr, wc, fr, fq);
;         if (!has_next) break;
; #pragma unroll
;         for (int a = 0; a < 2; ++a)
; #pragma unroll
;             for (int b = 0; b < 2; ++b)
; #pragma unroll
;                 for (int m = 0; m < 4; ++m)
; #pragma unroll
;                     for (int n = 0; n < 2; ++n) acc[a][b][m][n] = (f32x4){0.f, 0.f, 0.f, 0.f};
;         cur = nxt; cA = nA; cB = nB; ++ui;
;     }
;     PG8_WAIT_V(0);
;     if (wr == 0) PG8_BAR;
;     PG8_BAR;
;   __device__ __forceinline__ void operator()(const acc8_t& acc, const pg8::Unit& u, int wr, int wc, int fr, int fq) const {
;     const u16* GA = (const u16*)(ws + OFF_GA); u16* M = (u16*)(ws + OFF_M);
; #pragma unroll
;     for (int ai = 0; ai < 2; ai++)
; #pragma unroll
;       for (int m = 0; m < 4; m++) {
;         const size_t token = EPI_TOKEN(u, ai, m);
; #pragma unroll
;         for (int bj = 0; bj < 2; bj++)
; #pragma unroll
;           for (int n = 0; n < 2; n++) {
;             const int f = EPI_COL(u, bj, n);
;             const uint2 ga = *(const uint2*)(GA + token * 1024 + f);
;             uint2 o;
;             o.x = pack2(bflo(ga.x) * acc[ai][bj][m][n][0], bfhi(ga.x) * acc[ai][bj][m][n][1]);
;             o.y = pack2(bflo(ga.y) * acc[ai][bj][m][n][2], bfhi(ga.y) * acc[ai][bj][m][n][3]);
;             *(uint2*)(M + token * 1024 + f) = o;
;           }
;       }
	v_lshlrev_b32_e32 v222, 16, v190
	v_and_b32_e32 v223, 0xffff0000, v190
	v_pk_mul_f32 v[62:63], v[62:63], v[222:223]
	v_lshlrev_b32_e32 v224, 16, v191
	v_and_b32_e32 v225, 0xffff0000, v191
	v_pk_mul_f32 v[64:65], v[64:65], v[224:225]
	v_lshlrev_b32_e32 v226, 16, v192
	v_and_b32_e32 v227, 0xffff0000, v192
	v_pk_mul_f32 v[58:59], v[58:59], v[226:227]
	v_lshlrev_b32_e32 v228, 16, v193
	v_and_b32_e32 v229, 0xffff0000, v193
	v_pk_mul_f32 v[60:61], v[60:61], v[228:229]
	v_cvt_pk_bf16_f32 v138, v62, v63
	v_cvt_pk_bf16_f32 v139, v64, v65
	v_cvt_pk_bf16_f32 v140, v58, v59
	v_cvt_pk_bf16_f32 v141, v60, v61
	v_lshlrev_b32_e32 v222, 16, v194
	v_and_b32_e32 v223, 0xffff0000, v194
	v_pk_mul_f32 v[54:55], v[54:55], v[222:223]
	v_lshlrev_b32_e32 v224, 16, v195
	v_and_b32_e32 v225, 0xffff0000, v195
	v_pk_mul_f32 v[56:57], v[56:57], v[224:225]
	v_lshlrev_b32_e32 v226, 16, v196
	v_and_b32_e32 v227, 0xffff0000, v196
	v_pk_mul_f32 v[46:47], v[46:47], v[226:227]
	v_lshlrev_b32_e32 v228, 16, v197
	v_and_b32_e32 v229, 0xffff0000, v197
	v_pk_mul_f32 v[48:49], v[48:49], v[228:229]
	v_cvt_pk_bf16_f32 v142, v54, v55
	v_cvt_pk_bf16_f32 v143, v56, v57
	v_cvt_pk_bf16_f32 v144, v46, v47
	v_cvt_pk_bf16_f32 v145, v48, v49
	global_store_dwordx4 v[234:235], v[138:141], off
	global_store_dwordx4 v[234:235], v[142:145], off offset:256
	s_mov_b64 s[4:5], 0x8000
	v_lshl_add_u64 v[234:235], v[234:235], 0, s[4:5]
	v_permlane16_swap_b32_e32 v50, v42
	v_permlane16_swap_b32_e32 v51, v43
	v_permlane16_swap_b32_e32 v52, v44
	v_permlane16_swap_b32_e32 v53, v45
	v_permlane16_swap_b32_e32 v38, v34
	v_permlane16_swap_b32_e32 v39, v35
	v_permlane16_swap_b32_e32 v40, v36
	v_permlane16_swap_b32_e32 v41, v37
	s_mov_b64 s[4:5], 0x8000
	v_lshl_add_u64 v[230:231], v[230:231], 0, s[4:5]
	global_load_dwordx4 v[190:193], v[230:231], off
	global_load_dwordx4 v[194:197], v[230:231], off offset:256
	s_waitcnt vmcnt(8)
	v_lshlrev_b32_e32 v222, 16, v206
	v_and_b32_e32 v223, 0xffff0000, v206
	v_pk_mul_f32 v[50:51], v[50:51], v[222:223]
	v_lshlrev_b32_e32 v224, 16, v207
	v_and_b32_e32 v225, 0xffff0000, v207
	v_pk_mul_f32 v[52:53], v[52:53], v[224:225]
	v_lshlrev_b32_e32 v226, 16, v208
	v_and_b32_e32 v227, 0xffff0000, v208
	v_pk_mul_f32 v[42:43], v[42:43], v[226:227]
	v_lshlrev_b32_e32 v228, 16, v209
	v_and_b32_e32 v229, 0xffff0000, v209
	v_pk_mul_f32 v[44:45], v[44:45], v[228:229]
	v_cvt_pk_bf16_f32 v138, v50, v51
	v_cvt_pk_bf16_f32 v139, v52, v53
	v_cvt_pk_bf16_f32 v140, v42, v43
	v_cvt_pk_bf16_f32 v141, v44, v45
	v_lshlrev_b32_e32 v222, 16, v210
	v_and_b32_e32 v223, 0xffff0000, v210
	v_pk_mul_f32 v[38:39], v[38:39], v[222:223]
	v_lshlrev_b32_e32 v224, 16, v211
	v_and_b32_e32 v225, 0xffff0000, v211
	v_pk_mul_f32 v[40:41], v[40:41], v[224:225]
	v_lshlrev_b32_e32 v226, 16, v212
	v_and_b32_e32 v227, 0xffff0000, v212
	v_pk_mul_f32 v[34:35], v[34:35], v[226:227]
	v_lshlrev_b32_e32 v228, 16, v213
	v_and_b32_e32 v229, 0xffff0000, v213
	v_pk_mul_f32 v[36:37], v[36:37], v[228:229]
	v_cvt_pk_bf16_f32 v142, v38, v39
	v_cvt_pk_bf16_f32 v143, v40, v41
	v_cvt_pk_bf16_f32 v144, v34, v35
	v_cvt_pk_bf16_f32 v145, v36, v37
	global_store_dwordx4 v[234:235], v[138:141], off
	global_store_dwordx4 v[234:235], v[142:145], off offset:256
	s_mov_b64 s[4:5], 0x8000
	v_lshl_add_u64 v[234:235], v[234:235], 0, s[4:5]
	v_permlane16_swap_b32_e32 v30, v26
	v_permlane16_swap_b32_e32 v31, v27
	v_permlane16_swap_b32_e32 v32, v28
	v_permlane16_swap_b32_e32 v33, v29
	v_permlane16_swap_b32_e32 v22, v18
	v_permlane16_swap_b32_e32 v23, v19
	v_permlane16_swap_b32_e32 v24, v20
	v_permlane16_swap_b32_e32 v25, v21
	s_waitcnt vmcnt(6)
	v_lshlrev_b32_e32 v222, 16, v174
	v_and_b32_e32 v223, 0xffff0000, v174
	v_pk_mul_f32 v[30:31], v[30:31], v[222:223]
	v_lshlrev_b32_e32 v224, 16, v175
	v_and_b32_e32 v225, 0xffff0000, v175
	v_pk_mul_f32 v[32:33], v[32:33], v[224:225]
	v_lshlrev_b32_e32 v226, 16, v176
	v_and_b32_e32 v227, 0xffff0000, v176
	v_pk_mul_f32 v[26:27], v[26:27], v[226:227]
	v_lshlrev_b32_e32 v228, 16, v177
	v_and_b32_e32 v229, 0xffff0000, v177
	v_pk_mul_f32 v[28:29], v[28:29], v[228:229]
	v_cvt_pk_bf16_f32 v138, v30, v31
	v_cvt_pk_bf16_f32 v139, v32, v33
	v_cvt_pk_bf16_f32 v140, v26, v27
	v_cvt_pk_bf16_f32 v141, v28, v29
	v_lshlrev_b32_e32 v222, 16, v178
	v_and_b32_e32 v223, 0xffff0000, v178
	v_pk_mul_f32 v[22:23], v[22:23], v[222:223]
	v_lshlrev_b32_e32 v224, 16, v179
	v_and_b32_e32 v225, 0xffff0000, v179
	v_pk_mul_f32 v[24:25], v[24:25], v[224:225]
	v_lshlrev_b32_e32 v226, 16, v180
	v_and_b32_e32 v227, 0xffff0000, v180
	v_pk_mul_f32 v[18:19], v[18:19], v[226:227]
	v_lshlrev_b32_e32 v228, 16, v181
	v_and_b32_e32 v229, 0xffff0000, v181
	v_pk_mul_f32 v[20:21], v[20:21], v[228:229]
	v_cvt_pk_bf16_f32 v142, v22, v23
	v_cvt_pk_bf16_f32 v143, v24, v25
	v_cvt_pk_bf16_f32 v144, v18, v19
	v_cvt_pk_bf16_f32 v145, v20, v21
	global_store_dwordx4 v[234:235], v[138:141], off
	global_store_dwordx4 v[234:235], v[142:145], off offset:256
	s_mov_b64 s[4:5], 0x8000
	v_lshl_add_u64 v[234:235], v[234:235], 0, s[4:5]
	v_permlane16_swap_b32_e32 v14, v10
	v_permlane16_swap_b32_e32 v15, v11
	v_permlane16_swap_b32_e32 v16, v12
	v_permlane16_swap_b32_e32 v17, v13
	v_permlane16_swap_b32_e32 v6, v2
	v_permlane16_swap_b32_e32 v7, v3
	v_permlane16_swap_b32_e32 v8, v4
	v_permlane16_swap_b32_e32 v9, v5
	s_waitcnt vmcnt(4)
	v_lshlrev_b32_e32 v222, 16, v190
	v_and_b32_e32 v223, 0xffff0000, v190
	v_pk_mul_f32 v[14:15], v[14:15], v[222:223]
	v_lshlrev_b32_e32 v224, 16, v191
	v_and_b32_e32 v225, 0xffff0000, v191
	v_pk_mul_f32 v[16:17], v[16:17], v[224:225]
	v_lshlrev_b32_e32 v226, 16, v192
	v_and_b32_e32 v227, 0xffff0000, v192
	v_pk_mul_f32 v[10:11], v[10:11], v[226:227]
	v_lshlrev_b32_e32 v228, 16, v193
	v_and_b32_e32 v229, 0xffff0000, v193
	v_pk_mul_f32 v[12:13], v[12:13], v[228:229]
	v_cvt_pk_bf16_f32 v138, v14, v15
	v_cvt_pk_bf16_f32 v139, v16, v17
	v_cvt_pk_bf16_f32 v140, v10, v11
	v_cvt_pk_bf16_f32 v141, v12, v13
	v_lshlrev_b32_e32 v222, 16, v194
	v_and_b32_e32 v223, 0xffff0000, v194
	v_pk_mul_f32 v[6:7], v[6:7], v[222:223]
	v_lshlrev_b32_e32 v224, 16, v195
	v_and_b32_e32 v225, 0xffff0000, v195
	v_pk_mul_f32 v[8:9], v[8:9], v[224:225]
	v_lshlrev_b32_e32 v226, 16, v196
	v_and_b32_e32 v227, 0xffff0000, v196
	v_pk_mul_f32 v[2:3], v[2:3], v[226:227]
	v_lshlrev_b32_e32 v228, 16, v197
	v_and_b32_e32 v229, 0xffff0000, v197
	v_pk_mul_f32 v[4:5], v[4:5], v[228:229]
	v_cvt_pk_bf16_f32 v142, v6, v7
	v_cvt_pk_bf16_f32 v143, v8, v9
	v_cvt_pk_bf16_f32 v144, v2, v3
	v_cvt_pk_bf16_f32 v145, v4, v5
	global_store_dwordx4 v[234:235], v[138:141], off
	global_store_dwordx4 v[234:235], v[142:145], off offset:256
	s_and_b64 vcc, exec, s[18:19]
	s_cbranch_vccz .LBB0_688
	s_waitcnt vmcnt(0)
	s_cmpk_gt_u32 s33, 0xff
	s_cbranch_scc1 .LBB0_698
	s_barrier

; __device__ __forceinline__ float bflo(uint32_t v) { return __uint_as_float(v << 16); }
; __device__ __forceinline__ float bfhi(uint32_t v) { return __uint_as_float(v & 0xFFFF0000u); }
;   __device__ __forceinline__ void operator()(const acc8_t& acc, const pg8::Unit& u, int wr, int wc, int fr, int fq) const {
;     const u16* GB = (const u16*)(ws + OFF_GB); u16* M = (u16*)(ws + OFF_M);
; #pragma unroll
;     for (int ai = 0; ai < 2; ai++)
; #pragma unroll
;       for (int m = 0; m < 4; m++) {
;         const size_t token = EPI_TOKEN(u, ai, m);
; #pragma unroll
;         for (int bj = 0; bj < 2; bj++)
; #pragma unroll
;           for (int n = 0; n < 2; n++) {
;             const int f = EPI_COL(u, bj, n);
;             const uint2 gb = *(const uint2*)(GB + token * 1024 + f);
;             const uint2 mo = *(const uint2*)(M + token * 1024 + f);
;             uint2 o;
;             o.x = pack2(bflo(mo.x) + bflo(gb.x) * acc[ai][bj][m][n][0], bfhi(mo.x) + bfhi(gb.x) * acc[ai][bj][m][n][1]);
;             o.y = pack2(bflo(mo.y) + bflo(gb.y) * acc[ai][bj][m][n][2], bfhi(mo.y) + bfhi(gb.y) * acc[ai][bj][m][n][3]);
;             *(uint2*)(M + token * 1024 + f) = o;
;           }
;       }
;   }
.Lp4r_go:
	v_lshl_add_u32 v138, s24, 8, v154
	v_lshl_or_b32 v140, s22, 8, v156
	v_ashrrev_i32_e32 v139, 31, v138
	v_ashrrev_i32_e32 v141, 31, v140
	v_lshlrev_b64 v[142:143], 11, v[138:139]
	v_lshlrev_b64 v[140:141], 1, v[140:141]
	v_bfe_u32 v144, v0, 4, 1
	v_mov_b32_e32 v145, 0
	v_mul_u32_u24_e32 v144, 24, v144
	v_lshl_add_u64 v[142:143], v[142:143], 0, v[140:141]
	v_lshl_add_u64 v[142:143], v[142:143], 0, v[144:145]
	v_lshl_add_u64 v[230:231], s[8:9], 0, v[142:143]
	v_lshl_add_u64 v[234:235], s[10:11], 0, v[142:143]
	v_lshl_add_u64 v[232:233], s[10:11], 0, v[142:143]
	s_mov_b32 s22, s12
	s_mov_b32 s24, s14
	s_mov_b64 s[28:29], s[20:21]
	s_mov_b64 s[26:27], s[18:19]
	global_load_dwordx4 v[174:177], v[230:231], off
	global_load_dwordx4 v[178:181], v[230:231], off offset:256
	global_load_dwordx4 v[182:185], v[232:233], off
	global_load_dwordx4 v[186:189], v[232:233], off offset:256
	s_mov_b64 s[4:5], 0x8000
	v_lshl_add_u64 v[230:231], v[230:231], 0, s[4:5]
	v_lshl_add_u64 v[232:233], v[232:233], 0, s[4:5]
	global_load_dwordx4 v[190:193], v[230:231], off
	global_load_dwordx4 v[194:197], v[230:231], off offset:256
	global_load_dwordx4 v[198:201], v[232:233], off
	global_load_dwordx4 v[202:205], v[232:233], off offset:256
	v_permlane16_swap_b32_e32 v126, v122
	v_permlane16_swap_b32_e32 v127, v123
	v_permlane16_swap_b32_e32 v128, v124
	v_permlane16_swap_b32_e32 v129, v125
	v_permlane16_swap_b32_e32 v118, v114
	v_permlane16_swap_b32_e32 v119, v115
	v_permlane16_swap_b32_e32 v120, v116
	v_permlane16_swap_b32_e32 v121, v117
	s_mov_b64 s[4:5], 0x8000
	v_lshl_add_u64 v[230:231], v[230:231], 0, s[4:5]
	v_lshl_add_u64 v[232:233], v[232:233], 0, s[4:5]
	global_load_dwordx4 v[206:209], v[230:231], off
	global_load_dwordx4 v[210:213], v[230:231], off offset:256
	global_load_dwordx4 v[214:217], v[232:233], off
	global_load_dwordx4 v[218:221], v[232:233], off offset:256
	s_waitcnt vmcnt(8)
	v_lshlrev_b32_e32 v222, 16, v174
	v_and_b32_e32 v223, 0xffff0000, v174
	v_lshlrev_b32_e32 v146, 16, v182
	v_and_b32_e32 v147, 0xffff0000, v182
	v_pk_fma_f32 v[126:127], v[126:127], v[222:223], v[146:147]
	v_lshlrev_b32_e32 v224, 16, v175
	v_and_b32_e32 v225, 0xffff0000, v175
	v_lshlrev_b32_e32 v148, 16, v183
	v_and_b32_e32 v149, 0xffff0000, v183
	v_pk_fma_f32 v[128:129], v[128:129], v[224:225], v[148:149]
	v_lshlrev_b32_e32 v226, 16, v176
	v_and_b32_e32 v227, 0xffff0000, v176
	v_lshlrev_b32_e32 v150, 16, v184
	v_and_b32_e32 v151, 0xffff0000, v184
	v_pk_fma_f32 v[122:123], v[122:123], v[226:227], v[150:151]
	v_lshlrev_b32_e32 v228, 16, v177
	v_and_b32_e32 v229, 0xffff0000, v177
	v_lshlrev_b32_e32 v152, 16, v185
	v_and_b32_e32 v153, 0xffff0000, v185
	v_pk_fma_f32 v[124:125], v[124:125], v[228:229], v[152:153]
	v_cvt_pk_bf16_f32 v138, v126, v127
	v_cvt_pk_bf16_f32 v139, v128, v129
	v_cvt_pk_bf16_f32 v140, v122, v123
	v_cvt_pk_bf16_f32 v141, v124, v125
	v_lshlrev_b32_e32 v222, 16, v178
	v_and_b32_e32 v223, 0xffff0000, v178
	v_lshlrev_b32_e32 v146, 16, v186
	v_and_b32_e32 v147, 0xffff0000, v186
	v_pk_fma_f32 v[118:119], v[118:119], v[222:223], v[146:147]
	v_lshlrev_b32_e32 v224, 16, v179
	v_and_b32_e32 v225, 0xffff0000, v179
	v_lshlrev_b32_e32 v148, 16, v187
	v_and_b32_e32 v149, 0xffff0000, v187
	v_pk_fma_f32 v[120:121], v[120:121], v[224:225], v[148:149]
	v_lshlrev_b32_e32 v226, 16, v180
	v_and_b32_e32 v227, 0xffff0000, v180
	v_lshlrev_b32_e32 v150, 16, v188
	v_and_b32_e32 v151, 0xffff0000, v188
	v_pk_fma_f32 v[114:115], v[114:115], v[226:227], v[150:151]
	v_lshlrev_b32_e32 v228, 16, v181
	v_and_b32_e32 v229, 0xffff0000, v181
	v_lshlrev_b32_e32 v152, 16, v189
	v_and_b32_e32 v153, 0xffff0000, v189
	v_pk_fma_f32 v[116:117], v[116:117], v[228:229], v[152:153]
	v_cvt_pk_bf16_f32 v142, v118, v119
	v_cvt_pk_bf16_f32 v143, v120, v121
	v_cvt_pk_bf16_f32 v144, v114, v115
	v_cvt_pk_bf16_f32 v145, v116, v117
	global_store_dwordx4 v[234:235], v[138:141], off
	global_store_dwordx4 v[234:235], v[142:145], off offset:256
	s_mov_b64 s[4:5], 0x8000
	v_lshl_add_u64 v[234:235], v[234:235], 0, s[4:5]
	v_permlane16_swap_b32_e32 v110, v106
	v_permlane16_swap_b32_e32 v111, v107
	v_permlane16_swap_b32_e32 v112, v108
	v_permlane16_swap_b32_e32 v113, v109
	v_permlane16_swap_b32_e32 v102, v94
	v_permlane16_swap_b32_e32 v103, v95
	v_permlane16_swap_b32_e32 v104, v96
	v_permlane16_swap_b32_e32 v105, v97
	s_mov_b64 s[4:5], 0x8000
	v_lshl_add_u64 v[230:231], v[230:231], 0, s[4:5]
	v_lshl_add_u64 v[232:233], v[232:233], 0, s[4:5]
	global_load_dwordx4 v[174:177], v[230:231], off
	global_load_dwordx4 v[178:181], v[230:231], off offset:256
	global_load_dwordx4 v[182:185], v[232:233], off
	global_load_dwordx4 v[186:189], v[232:233], off offset:256
	s_waitcnt vmcnt(10)
; __device__ __forceinline__ float bflo(uint32_t v) { return __uint_as_float(v << 16); }
; __device__ __forceinline__ float bfhi(uint32_t v) { return __uint_as_float(v & 0xFFFF0000u); }
;   __device__ __forceinline__ void operator()(const acc8_t& acc, const pg8::Unit& u, int wr, int wc, int fr, int fq) const {
;     const u16* GB = (const u16*)(ws + OFF_GB); u16* M = (u16*)(ws + OFF_M);
; #pragma unroll
;     for (int ai = 0; ai < 2; ai++)
; #pragma unroll
;       for (int m = 0; m < 4; m++) {
;         const size_t token = EPI_TOKEN(u, ai, m);
; #pragma unroll
;         for (int bj = 0; bj < 2; bj++)
; #pragma unroll
;           for (int n = 0; n < 2; n++) {
;             const int f = EPI_COL(u, bj, n);
;             const uint2 gb = *(const uint2*)(GB + token * 1024 + f);
;             const uint2 mo = *(const uint2*)(M + token * 1024 + f);
;             uint2 o;
;             o.x = pack2(bflo(mo.x) + bflo(gb.x) * acc[ai][bj][m][n][0], bfhi(mo.x) + bfhi(gb.x) * acc[ai][bj][m][n][1]);
;             o.y = pack2(bflo(mo.y) + bflo(gb.y) * acc[ai][bj][m][n][2], bfhi(mo.y) + bfhi(gb.y) * acc[ai][bj][m][n][3]);
;             *(uint2*)(M + token * 1024 + f) = o;
;           }
;       }
;   }
	v_lshlrev_b32_e32 v222, 16, v190
	v_and_b32_e32 v223, 0xffff0000, v190
	v_lshlrev_b32_e32 v146, 16, v198
	v_and_b32_e32 v147, 0xffff0000, v198
	v_pk_fma_f32 v[110:111], v[110:111], v[222:223], v[146:147]
	v_lshlrev_b32_e32 v224, 16, v191
	v_and_b32_e32 v225, 0xffff0000, v191
	v_lshlrev_b32_e32 v148, 16, v199
	v_and_b32_e32 v149, 0xffff0000, v199
	v_pk_fma_f32 v[112:113], v[112:113], v[224:225], v[148:149]
	v_lshlrev_b32_e32 v226, 16, v192
	v_and_b32_e32 v227, 0xffff0000, v192
	v_lshlrev_b32_e32 v150, 16, v200
	v_and_b32_e32 v151, 0xffff0000, v200
	v_pk_fma_f32 v[106:107], v[106:107], v[226:227], v[150:151]
	v_lshlrev_b32_e32 v228, 16, v193
	v_and_b32_e32 v229, 0xffff0000, v193
	v_lshlrev_b32_e32 v152, 16, v201
	v_and_b32_e32 v153, 0xffff0000, v201
	v_pk_fma_f32 v[108:109], v[108:109], v[228:229], v[152:153]
	v_cvt_pk_bf16_f32 v138, v110, v111
	v_cvt_pk_bf16_f32 v139, v112, v113
	v_cvt_pk_bf16_f32 v140, v106, v107
	v_cvt_pk_bf16_f32 v141, v108, v109
	v_lshlrev_b32_e32 v222, 16, v194
	v_and_b32_e32 v223, 0xffff0000, v194
	v_lshlrev_b32_e32 v146, 16, v202
	v_and_b32_e32 v147, 0xffff0000, v202
	v_pk_fma_f32 v[102:103], v[102:103], v[222:223], v[146:147]
	v_lshlrev_b32_e32 v224, 16, v195
	v_and_b32_e32 v225, 0xffff0000, v195
	v_lshlrev_b32_e32 v148, 16, v203
	v_and_b32_e32 v149, 0xffff0000, v203
	v_pk_fma_f32 v[104:105], v[104:105], v[224:225], v[148:149]
	v_lshlrev_b32_e32 v226, 16, v196
	v_and_b32_e32 v227, 0xffff0000, v196
	v_lshlrev_b32_e32 v150, 16, v204
	v_and_b32_e32 v151, 0xffff0000, v204
	v_pk_fma_f32 v[94:95], v[94:95], v[226:227], v[150:151]
	v_lshlrev_b32_e32 v228, 16, v197
	v_and_b32_e32 v229, 0xffff0000, v197
	v_lshlrev_b32_e32 v152, 16, v205
	v_and_b32_e32 v153, 0xffff0000, v205
	v_pk_fma_f32 v[96:97], v[96:97], v[228:229], v[152:153]
	v_cvt_pk_bf16_f32 v142, v102, v103
	v_cvt_pk_bf16_f32 v143, v104, v105
	v_cvt_pk_bf16_f32 v144, v94, v95
	v_cvt_pk_bf16_f32 v145, v96, v97
	global_store_dwordx4 v[234:235], v[138:141], off
	global_store_dwordx4 v[234:235], v[142:145], off offset:256
	s_mov_b64 s[4:5], 0x8000
	v_lshl_add_u64 v[234:235], v[234:235], 0, s[4:5]
	v_permlane16_swap_b32_e32 v98, v90
	v_permlane16_swap_b32_e32 v99, v91
	v_permlane16_swap_b32_e32 v100, v92
	v_permlane16_swap_b32_e32 v101, v93
	v_permlane16_swap_b32_e32 v78, v74
	v_permlane16_swap_b32_e32 v79, v75
	v_permlane16_swap_b32_e32 v80, v76
	v_permlane16_swap_b32_e32 v81, v77
	s_mov_b64 s[4:5], 0x28000
	v_lshl_add_u64 v[230:231], v[230:231], 0, s[4:5]
	v_lshl_add_u64 v[232:233], v[232:233], 0, s[4:5]
	global_load_dwordx4 v[190:193], v[230:231], off
	global_load_dwordx4 v[194:197], v[230:231], off offset:256
	global_load_dwordx4 v[198:201], v[232:233], off
	global_load_dwordx4 v[202:205], v[232:233], off offset:256
	s_waitcnt vmcnt(12)
	v_lshlrev_b32_e32 v222, 16, v206
	v_and_b32_e32 v223, 0xffff0000, v206
	v_lshlrev_b32_e32 v146, 16, v214
	v_and_b32_e32 v147, 0xffff0000, v214
	v_pk_fma_f32 v[98:99], v[98:99], v[222:223], v[146:147]
	v_lshlrev_b32_e32 v224, 16, v207
	v_and_b32_e32 v225, 0xffff0000, v207
	v_lshlrev_b32_e32 v148, 16, v215
	v_and_b32_e32 v149, 0xffff0000, v215
	v_pk_fma_f32 v[100:101], v[100:101], v[224:225], v[148:149]
	v_lshlrev_b32_e32 v226, 16, v208
	v_and_b32_e32 v227, 0xffff0000, v208
	v_lshlrev_b32_e32 v150, 16, v216
	v_and_b32_e32 v151, 0xffff0000, v216
	v_pk_fma_f32 v[90:91], v[90:91], v[226:227], v[150:151]
	v_lshlrev_b32_e32 v228, 16, v209
	v_and_b32_e32 v229, 0xffff0000, v209
	v_lshlrev_b32_e32 v152, 16, v217
	v_and_b32_e32 v153, 0xffff0000, v217
	v_pk_fma_f32 v[92:93], v[92:93], v[228:229], v[152:153]
	v_cvt_pk_bf16_f32 v138, v98, v99
	v_cvt_pk_bf16_f32 v139, v100, v101
	v_cvt_pk_bf16_f32 v140, v90, v91
	v_cvt_pk_bf16_f32 v141, v92, v93
	v_lshlrev_b32_e32 v222, 16, v210
	v_and_b32_e32 v223, 0xffff0000, v210
	v_lshlrev_b32_e32 v146, 16, v218
	v_and_b32_e32 v147, 0xffff0000, v218
	v_pk_fma_f32 v[78:79], v[78:79], v[222:223], v[146:147]
	v_lshlrev_b32_e32 v224, 16, v211
	v_and_b32_e32 v225, 0xffff0000, v211
	v_lshlrev_b32_e32 v148, 16, v219
	v_and_b32_e32 v149, 0xffff0000, v219
	v_pk_fma_f32 v[80:81], v[80:81], v[224:225], v[148:149]
	v_lshlrev_b32_e32 v226, 16, v212
	v_and_b32_e32 v227, 0xffff0000, v212
	v_lshlrev_b32_e32 v150, 16, v220
	v_and_b32_e32 v151, 0xffff0000, v220
	v_pk_fma_f32 v[74:75], v[74:75], v[226:227], v[150:151]
	v_lshlrev_b32_e32 v228, 16, v213
	v_and_b32_e32 v229, 0xffff0000, v213
	v_lshlrev_b32_e32 v152, 16, v221
	v_and_b32_e32 v153, 0xffff0000, v221
	v_pk_fma_f32 v[76:77], v[76:77], v[228:229], v[152:153]
	v_cvt_pk_bf16_f32 v142, v78, v79
	v_cvt_pk_bf16_f32 v143, v80, v81
	v_cvt_pk_bf16_f32 v144, v74, v75
	v_cvt_pk_bf16_f32 v145, v76, v77
	global_store_dwordx4 v[234:235], v[138:141], off
	global_store_dwordx4 v[234:235], v[142:145], off offset:256
	s_mov_b64 s[4:5], 0x8000
	v_lshl_add_u64 v[234:235], v[234:235], 0, s[4:5]
	v_permlane16_swap_b32_e32 v86, v82
	v_permlane16_swap_b32_e32 v87, v83
	v_permlane16_swap_b32_e32 v88, v84
	v_permlane16_swap_b32_e32 v89, v85
	v_permlane16_swap_b32_e32 v70, v66
	v_permlane16_swap_b32_e32 v71, v67
	v_permlane16_swap_b32_e32 v72, v68
	v_permlane16_swap_b32_e32 v73, v69
	s_mov_b64 s[4:5], 0x8000
	v_lshl_add_u64 v[230:231], v[230:231], 0, s[4:5]
	v_lshl_add_u64 v[232:233], v[232:233], 0, s[4:5]
	global_load_dwordx4 v[206:209], v[230:231], off
	global_load_dwordx4 v[210:213], v[230:231], off offset:256
	global_load_dwordx4 v[214:217], v[232:233], off
	global_load_dwordx4 v[218:221], v[232:233], off offset:256
	s_waitcnt vmcnt(12)
; __device__ __forceinline__ float bflo(uint32_t v) { return __uint_as_float(v << 16); }
; __device__ __forceinline__ float bfhi(uint32_t v) { return __uint_as_float(v & 0xFFFF0000u); }
;   __device__ __forceinline__ void operator()(const acc8_t& acc, const pg8::Unit& u, int wr, int wc, int fr, int fq) const {
;     const u16* GB = (const u16*)(ws + OFF_GB); u16* M = (u16*)(ws + OFF_M);
; #pragma unroll
;     for (int ai = 0; ai < 2; ai++)
; #pragma unroll
;       for (int m = 0; m < 4; m++) {
;         const size_t token = EPI_TOKEN(u, ai, m);
; #pragma unroll
;         for (int bj = 0; bj < 2; bj++)
; #pragma unroll
;           for (int n = 0; n < 2; n++) {
;             const int f = EPI_COL(u, bj, n);
;             const uint2 gb = *(const uint2*)(GB + token * 1024 + f);
;             const uint2 mo = *(const uint2*)(M + token * 1024 + f);
;             uint2 o;
;             o.x = pack2(bflo(mo.x) + bflo(gb.x) * acc[ai][bj][m][n][0], bfhi(mo.x) + bfhi(gb.x) * acc[ai][bj][m][n][1]);
;             o.y = pack2(bflo(mo.y) + bflo(gb.y) * acc[ai][bj][m][n][2], bfhi(mo.y) + bfhi(gb.y) * acc[ai][bj][m][n][3]);
;             *(uint2*)(M + token * 1024 + f) = o;
;           }
;       }
;   }
	v_lshlrev_b32_e32 v222, 16, v174
	v_and_b32_e32 v223, 0xffff0000, v174
	v_lshlrev_b32_e32 v146, 16, v182
	v_and_b32_e32 v147, 0xffff0000, v182
	v_pk_fma_f32 v[86:87], v[86:87], v[222:223], v[146:147]
	v_lshlrev_b32_e32 v224, 16, v175
	v_and_b32_e32 v225, 0xffff0000, v175
	v_lshlrev_b32_e32 v148, 16, v183
	v_and_b32_e32 v149, 0xffff0000, v183
	v_pk_fma_f32 v[88:89], v[88:89], v[224:225], v[148:149]
	v_lshlrev_b32_e32 v226, 16, v176
	v_and_b32_e32 v227, 0xffff0000, v176
	v_lshlrev_b32_e32 v150, 16, v184
	v_and_b32_e32 v151, 0xffff0000, v184
	v_pk_fma_f32 v[82:83], v[82:83], v[226:227], v[150:151]
	v_lshlrev_b32_e32 v228, 16, v177
	v_and_b32_e32 v229, 0xffff0000, v177
	v_lshlrev_b32_e32 v152, 16, v185
	v_and_b32_e32 v153, 0xffff0000, v185
	v_pk_fma_f32 v[84:85], v[84:85], v[228:229], v[152:153]
	v_cvt_pk_bf16_f32 v138, v86, v87
	v_cvt_pk_bf16_f32 v139, v88, v89
	v_cvt_pk_bf16_f32 v140, v82, v83
	v_cvt_pk_bf16_f32 v141, v84, v85
	v_lshlrev_b32_e32 v222, 16, v178
	v_and_b32_e32 v223, 0xffff0000, v178
	v_lshlrev_b32_e32 v146, 16, v186
	v_and_b32_e32 v147, 0xffff0000, v186
	v_pk_fma_f32 v[70:71], v[70:71], v[222:223], v[146:147]
	v_lshlrev_b32_e32 v224, 16, v179
	v_and_b32_e32 v225, 0xffff0000, v179
	v_lshlrev_b32_e32 v148, 16, v187
	v_and_b32_e32 v149, 0xffff0000, v187
	v_pk_fma_f32 v[72:73], v[72:73], v[224:225], v[148:149]
	v_lshlrev_b32_e32 v226, 16, v180
	v_and_b32_e32 v227, 0xffff0000, v180
	v_lshlrev_b32_e32 v150, 16, v188
	v_and_b32_e32 v151, 0xffff0000, v188
	v_pk_fma_f32 v[66:67], v[66:67], v[226:227], v[150:151]
	v_lshlrev_b32_e32 v228, 16, v181
	v_and_b32_e32 v229, 0xffff0000, v181
	v_lshlrev_b32_e32 v152, 16, v189
	v_and_b32_e32 v153, 0xffff0000, v189
	v_pk_fma_f32 v[68:69], v[68:69], v[228:229], v[152:153]
	v_cvt_pk_bf16_f32 v142, v70, v71
	v_cvt_pk_bf16_f32 v143, v72, v73
	v_cvt_pk_bf16_f32 v144, v66, v67
	v_cvt_pk_bf16_f32 v145, v68, v69
	global_store_dwordx4 v[234:235], v[138:141], off
	global_store_dwordx4 v[234:235], v[142:145], off offset:256
	s_mov_b64 s[4:5], 0x28000
	v_lshl_add_u64 v[234:235], v[234:235], 0, s[4:5]
	v_permlane16_swap_b32_e32 v62, v58
	v_permlane16_swap_b32_e32 v63, v59
	v_permlane16_swap_b32_e32 v64, v60
	v_permlane16_swap_b32_e32 v65, v61
	v_permlane16_swap_b32_e32 v54, v50
	v_permlane16_swap_b32_e32 v55, v51
	v_permlane16_swap_b32_e32 v56, v52
	v_permlane16_swap_b32_e32 v57, v53
	s_mov_b64 s[4:5], 0x8000
	v_lshl_add_u64 v[230:231], v[230:231], 0, s[4:5]
	v_lshl_add_u64 v[232:233], v[232:233], 0, s[4:5]
	global_load_dwordx4 v[174:177], v[230:231], off
	global_load_dwordx4 v[178:181], v[230:231], off offset:256
	global_load_dwordx4 v[182:185], v[232:233], off
	global_load_dwordx4 v[186:189], v[232:233], off offset:256
	s_waitcnt vmcnt(12)
	v_lshlrev_b32_e32 v222, 16, v190
	v_and_b32_e32 v223, 0xffff0000, v190
	v_lshlrev_b32_e32 v146, 16, v198
	v_and_b32_e32 v147, 0xffff0000, v198
	v_pk_fma_f32 v[62:63], v[62:63], v[222:223], v[146:147]
	v_lshlrev_b32_e32 v224, 16, v191
	v_and_b32_e32 v225, 0xffff0000, v191
	v_lshlrev_b32_e32 v148, 16, v199
	v_and_b32_e32 v149, 0xffff0000, v199
	v_pk_fma_f32 v[64:65], v[64:65], v[224:225], v[148:149]
	v_lshlrev_b32_e32 v226, 16, v192
	v_and_b32_e32 v227, 0xffff0000, v192
	v_lshlrev_b32_e32 v150, 16, v200
	v_and_b32_e32 v151, 0xffff0000, v200
	v_pk_fma_f32 v[58:59], v[58:59], v[226:227], v[150:151]
	v_lshlrev_b32_e32 v228, 16, v193
	v_and_b32_e32 v229, 0xffff0000, v193
	v_lshlrev_b32_e32 v152, 16, v201
	v_and_b32_e32 v153, 0xffff0000, v201
	v_pk_fma_f32 v[60:61], v[60:61], v[228:229], v[152:153]
	v_cvt_pk_bf16_f32 v138, v62, v63
	v_cvt_pk_bf16_f32 v139, v64, v65
	v_cvt_pk_bf16_f32 v140, v58, v59
	v_cvt_pk_bf16_f32 v141, v60, v61
	v_lshlrev_b32_e32 v222, 16, v194
	v_and_b32_e32 v223, 0xffff0000, v194
	v_lshlrev_b32_e32 v146, 16, v202
	v_and_b32_e32 v147, 0xffff0000, v202
	v_pk_fma_f32 v[54:55], v[54:55], v[222:223], v[146:147]
	v_lshlrev_b32_e32 v224, 16, v195
	v_and_b32_e32 v225, 0xffff0000, v195
	v_lshlrev_b32_e32 v148, 16, v203
	v_and_b32_e32 v149, 0xffff0000, v203
	v_pk_fma_f32 v[56:57], v[56:57], v[224:225], v[148:149]
	v_lshlrev_b32_e32 v226, 16, v196
	v_and_b32_e32 v227, 0xffff0000, v196
	v_lshlrev_b32_e32 v150, 16, v204
	v_and_b32_e32 v151, 0xffff0000, v204
	v_pk_fma_f32 v[50:51], v[50:51], v[226:227], v[150:151]
	v_lshlrev_b32_e32 v228, 16, v197
	v_and_b32_e32 v229, 0xffff0000, v197
	v_lshlrev_b32_e32 v152, 16, v205
	v_and_b32_e32 v153, 0xffff0000, v205
	v_pk_fma_f32 v[52:53], v[52:53], v[228:229], v[152:153]
	v_cvt_pk_bf16_f32 v142, v54, v55
	v_cvt_pk_bf16_f32 v143, v56, v57
	v_cvt_pk_bf16_f32 v144, v50, v51
	v_cvt_pk_bf16_f32 v145, v52, v53
	global_store_dwordx4 v[234:235], v[138:141], off
	global_store_dwordx4 v[234:235], v[142:145], off offset:256
	s_mov_b64 s[4:5], 0x8000
	v_lshl_add_u64 v[234:235], v[234:235], 0, s[4:5]
	v_permlane16_swap_b32_e32 v46, v42
	v_permlane16_swap_b32_e32 v47, v43
	v_permlane16_swap_b32_e32 v48, v44
	v_permlane16_swap_b32_e32 v49, v45
	v_permlane16_swap_b32_e32 v38, v34
	v_permlane16_swap_b32_e32 v39, v35
	v_permlane16_swap_b32_e32 v40, v36
	v_permlane16_swap_b32_e32 v41, v37
	s_mov_b64 s[4:5], 0x8000
	v_lshl_add_u64 v[230:231], v[230:231], 0, s[4:5]
	v_lshl_add_u64 v[232:233], v[232:233], 0, s[4:5]
	global_load_dwordx4 v[190:193], v[230:231], off
	global_load_dwordx4 v[194:197], v[230:231], off offset:256
	global_load_dwordx4 v[198:201], v[232:233], off
	global_load_dwordx4 v[202:205], v[232:233], off offset:256
	s_waitcnt vmcnt(12)
; __device__ __forceinline__ float bflo(uint32_t v) { return __uint_as_float(v << 16); }
; __device__ __forceinline__ float bfhi(uint32_t v) { return __uint_as_float(v & 0xFFFF0000u); }
; #define PG8_WAIT_V(n) asm volatile("s_waitcnt vmcnt(" #n ")" ::: "memory")
; #define PG8_BAR __builtin_amdgcn_s_barrier()
; template <class Epi, class Sched>
; __device__ __forceinline__ void gemm_phase(PG8_LAS unsigned char* lds, const Gemm g, const Sched& S, const Epi& E) {
;     ...
;         E(acc, cur, wr, wc, fr, fq);
;         if (!has_next) break;
; #pragma unroll
;         for (int a = 0; a < 2; ++a)
; #pragma unroll
;             for (int b = 0; b < 2; ++b)
; #pragma unroll
;                 for (int m = 0; m < 4; ++m)
; #pragma unroll
;                     for (int n = 0; n < 2; ++n) acc[a][b][m][n] = (f32x4){0.f, 0.f, 0.f, 0.f};
;         cur = nxt; cA = nA; cB = nB; ++ui;
;     }
;     PG8_WAIT_V(0);
;     if (wr == 0) PG8_BAR;
;     PG8_BAR;
;   __device__ __forceinline__ void operator()(const acc8_t& acc, const pg8::Unit& u, int wr, int wc, int fr, int fq) const {
;     const u16* GB = (const u16*)(ws + OFF_GB); u16* M = (u16*)(ws + OFF_M);
; #pragma unroll
;     for (int ai = 0; ai < 2; ai++)
; #pragma unroll
;       for (int m = 0; m < 4; m++) {
;         const size_t token = EPI_TOKEN(u, ai, m);
; #pragma unroll
;         for (int bj = 0; bj < 2; bj++)
; #pragma unroll
;           for (int n = 0; n < 2; n++) {
;             const int f = EPI_COL(u, bj, n);
;             const uint2 gb = *(const uint2*)(GB + token * 1024 + f);
;             const uint2 mo = *(const uint2*)(M + token * 1024 + f);
;             uint2 o;
;             o.x = pack2(bflo(mo.x) + bflo(gb.x) * acc[ai][bj][m][n][0], bfhi(mo.x) + bfhi(gb.x) * acc[ai][bj][m][n][1]);
;             o.y = pack2(bflo(mo.y) + bflo(gb.y) * acc[ai][bj][m][n][2], bfhi(mo.y) + bfhi(gb.y) * acc[ai][bj][m][n][3]);
;             *(uint2*)(M + token * 1024 + f) = o;
;           }
;       }
;   }
	v_lshlrev_b32_e32 v222, 16, v206
	v_and_b32_e32 v223, 0xffff0000, v206
	v_lshlrev_b32_e32 v146, 16, v214
	v_and_b32_e32 v147, 0xffff0000, v214
	v_pk_fma_f32 v[46:47], v[46:47], v[222:223], v[146:147]
	v_lshlrev_b32_e32 v224, 16, v207
	v_and_b32_e32 v225, 0xffff0000, v207
	v_lshlrev_b32_e32 v148, 16, v215
	v_and_b32_e32 v149, 0xffff0000, v215
	v_pk_fma_f32 v[48:49], v[48:49], v[224:225], v[148:149]
	v_lshlrev_b32_e32 v226, 16, v208
	v_and_b32_e32 v227, 0xffff0000, v208
	v_lshlrev_b32_e32 v150, 16, v216
	v_and_b32_e32 v151, 0xffff0000, v216
	v_pk_fma_f32 v[42:43], v[42:43], v[226:227], v[150:151]
	v_lshlrev_b32_e32 v228, 16, v209
	v_and_b32_e32 v229, 0xffff0000, v209
	v_lshlrev_b32_e32 v152, 16, v217
	v_and_b32_e32 v153, 0xffff0000, v217
	v_pk_fma_f32 v[44:45], v[44:45], v[228:229], v[152:153]
	v_cvt_pk_bf16_f32 v138, v46, v47
	v_cvt_pk_bf16_f32 v139, v48, v49
	v_cvt_pk_bf16_f32 v140, v42, v43
	v_cvt_pk_bf16_f32 v141, v44, v45
	v_lshlrev_b32_e32 v222, 16, v210
	v_and_b32_e32 v223, 0xffff0000, v210
	v_lshlrev_b32_e32 v146, 16, v218
	v_and_b32_e32 v147, 0xffff0000, v218
	v_pk_fma_f32 v[38:39], v[38:39], v[222:223], v[146:147]
	v_lshlrev_b32_e32 v224, 16, v211
	v_and_b32_e32 v225, 0xffff0000, v211
	v_lshlrev_b32_e32 v148, 16, v219
	v_and_b32_e32 v149, 0xffff0000, v219
	v_pk_fma_f32 v[40:41], v[40:41], v[224:225], v[148:149]
	v_lshlrev_b32_e32 v226, 16, v212
	v_and_b32_e32 v227, 0xffff0000, v212
	v_lshlrev_b32_e32 v150, 16, v220
	v_and_b32_e32 v151, 0xffff0000, v220
	v_pk_fma_f32 v[34:35], v[34:35], v[226:227], v[150:151]
	v_lshlrev_b32_e32 v228, 16, v213
	v_and_b32_e32 v229, 0xffff0000, v213
	v_lshlrev_b32_e32 v152, 16, v221
	v_and_b32_e32 v153, 0xffff0000, v221
	v_pk_fma_f32 v[36:37], v[36:37], v[228:229], v[152:153]
	v_cvt_pk_bf16_f32 v142, v38, v39
	v_cvt_pk_bf16_f32 v143, v40, v41
	v_cvt_pk_bf16_f32 v144, v34, v35
	v_cvt_pk_bf16_f32 v145, v36, v37
	global_store_dwordx4 v[234:235], v[138:141], off
	global_store_dwordx4 v[234:235], v[142:145], off offset:256
	s_mov_b64 s[4:5], 0x8000
	v_lshl_add_u64 v[234:235], v[234:235], 0, s[4:5]
	v_permlane16_swap_b32_e32 v30, v26
	v_permlane16_swap_b32_e32 v31, v27
	v_permlane16_swap_b32_e32 v32, v28
	v_permlane16_swap_b32_e32 v33, v29
	v_permlane16_swap_b32_e32 v22, v18
	v_permlane16_swap_b32_e32 v23, v19
	v_permlane16_swap_b32_e32 v24, v20
	v_permlane16_swap_b32_e32 v25, v21
	s_waitcnt vmcnt(8)
	v_lshlrev_b32_e32 v222, 16, v174
	v_and_b32_e32 v223, 0xffff0000, v174
	v_lshlrev_b32_e32 v146, 16, v182
	v_and_b32_e32 v147, 0xffff0000, v182
	v_pk_fma_f32 v[30:31], v[30:31], v[222:223], v[146:147]
	v_lshlrev_b32_e32 v224, 16, v175
	v_and_b32_e32 v225, 0xffff0000, v175
	v_lshlrev_b32_e32 v148, 16, v183
	v_and_b32_e32 v149, 0xffff0000, v183
	v_pk_fma_f32 v[32:33], v[32:33], v[224:225], v[148:149]
	v_lshlrev_b32_e32 v226, 16, v176
	v_and_b32_e32 v227, 0xffff0000, v176
	v_lshlrev_b32_e32 v150, 16, v184
	v_and_b32_e32 v151, 0xffff0000, v184
	v_pk_fma_f32 v[26:27], v[26:27], v[226:227], v[150:151]
	v_lshlrev_b32_e32 v228, 16, v177
	v_and_b32_e32 v229, 0xffff0000, v177
	v_lshlrev_b32_e32 v152, 16, v185
	v_and_b32_e32 v153, 0xffff0000, v185
	v_pk_fma_f32 v[28:29], v[28:29], v[228:229], v[152:153]
	v_cvt_pk_bf16_f32 v138, v30, v31
	v_cvt_pk_bf16_f32 v139, v32, v33
	v_cvt_pk_bf16_f32 v140, v26, v27
	v_cvt_pk_bf16_f32 v141, v28, v29
	v_lshlrev_b32_e32 v222, 16, v178
	v_and_b32_e32 v223, 0xffff0000, v178
	v_lshlrev_b32_e32 v146, 16, v186
	v_and_b32_e32 v147, 0xffff0000, v186
	v_pk_fma_f32 v[22:23], v[22:23], v[222:223], v[146:147]
	v_lshlrev_b32_e32 v224, 16, v179
	v_and_b32_e32 v225, 0xffff0000, v179
	v_lshlrev_b32_e32 v148, 16, v187
	v_and_b32_e32 v149, 0xffff0000, v187
	v_pk_fma_f32 v[24:25], v[24:25], v[224:225], v[148:149]
	v_lshlrev_b32_e32 v226, 16, v180
	v_and_b32_e32 v227, 0xffff0000, v180
	v_lshlrev_b32_e32 v150, 16, v188
	v_and_b32_e32 v151, 0xffff0000, v188
	v_pk_fma_f32 v[18:19], v[18:19], v[226:227], v[150:151]
	v_lshlrev_b32_e32 v228, 16, v181
	v_and_b32_e32 v229, 0xffff0000, v181
	v_lshlrev_b32_e32 v152, 16, v189
	v_and_b32_e32 v153, 0xffff0000, v189
	v_pk_fma_f32 v[20:21], v[20:21], v[228:229], v[152:153]
	v_cvt_pk_bf16_f32 v142, v22, v23
	v_cvt_pk_bf16_f32 v143, v24, v25
	v_cvt_pk_bf16_f32 v144, v18, v19
	v_cvt_pk_bf16_f32 v145, v20, v21
	global_store_dwordx4 v[234:235], v[138:141], off
	global_store_dwordx4 v[234:235], v[142:145], off offset:256
	s_mov_b64 s[4:5], 0x8000
	v_lshl_add_u64 v[234:235], v[234:235], 0, s[4:5]
	v_permlane16_swap_b32_e32 v14, v10
	v_permlane16_swap_b32_e32 v15, v11
	v_permlane16_swap_b32_e32 v16, v12
	v_permlane16_swap_b32_e32 v17, v13
	v_permlane16_swap_b32_e32 v6, v2
	v_permlane16_swap_b32_e32 v7, v3
	v_permlane16_swap_b32_e32 v8, v4
	v_permlane16_swap_b32_e32 v9, v5
	s_waitcnt vmcnt(4)
	v_lshlrev_b32_e32 v222, 16, v190
	v_and_b32_e32 v223, 0xffff0000, v190
	v_lshlrev_b32_e32 v146, 16, v198
	v_and_b32_e32 v147, 0xffff0000, v198
	v_pk_fma_f32 v[14:15], v[14:15], v[222:223], v[146:147]
	v_lshlrev_b32_e32 v224, 16, v191
	v_and_b32_e32 v225, 0xffff0000, v191
	v_lshlrev_b32_e32 v148, 16, v199
	v_and_b32_e32 v149, 0xffff0000, v199
	v_pk_fma_f32 v[16:17], v[16:17], v[224:225], v[148:149]
	v_lshlrev_b32_e32 v226, 16, v192
	v_and_b32_e32 v227, 0xffff0000, v192
	v_lshlrev_b32_e32 v150, 16, v200
	v_and_b32_e32 v151, 0xffff0000, v200
	v_pk_fma_f32 v[10:11], v[10:11], v[226:227], v[150:151]
	v_lshlrev_b32_e32 v228, 16, v193
	v_and_b32_e32 v229, 0xffff0000, v193
	v_lshlrev_b32_e32 v152, 16, v201
	v_and_b32_e32 v153, 0xffff0000, v201
	v_pk_fma_f32 v[12:13], v[12:13], v[228:229], v[152:153]
	v_cvt_pk_bf16_f32 v138, v14, v15
	v_cvt_pk_bf16_f32 v139, v16, v17
	v_cvt_pk_bf16_f32 v140, v10, v11
	v_cvt_pk_bf16_f32 v141, v12, v13
	v_lshlrev_b32_e32 v222, 16, v194
	v_and_b32_e32 v223, 0xffff0000, v194
	v_lshlrev_b32_e32 v146, 16, v202
	v_and_b32_e32 v147, 0xffff0000, v202
	v_pk_fma_f32 v[6:7], v[6:7], v[222:223], v[146:147]
	v_lshlrev_b32_e32 v224, 16, v195
	v_and_b32_e32 v225, 0xffff0000, v195
	v_lshlrev_b32_e32 v148, 16, v203
	v_and_b32_e32 v149, 0xffff0000, v203
	v_pk_fma_f32 v[8:9], v[8:9], v[224:225], v[148:149]
	v_lshlrev_b32_e32 v226, 16, v196
	v_and_b32_e32 v227, 0xffff0000, v196
	v_lshlrev_b32_e32 v150, 16, v204
	v_and_b32_e32 v151, 0xffff0000, v204
	v_pk_fma_f32 v[2:3], v[2:3], v[226:227], v[150:151]
	v_lshlrev_b32_e32 v228, 16, v197
	v_and_b32_e32 v229, 0xffff0000, v197
	v_lshlrev_b32_e32 v152, 16, v205
	v_and_b32_e32 v153, 0xffff0000, v205
	v_pk_fma_f32 v[4:5], v[4:5], v[228:229], v[152:153]
	v_cvt_pk_bf16_f32 v142, v6, v7
	v_cvt_pk_bf16_f32 v143, v8, v9
	v_cvt_pk_bf16_f32 v144, v2, v3
	v_cvt_pk_bf16_f32 v145, v4, v5
	global_store_dwordx4 v[234:235], v[138:141], off
	global_store_dwordx4 v[234:235], v[142:145], off offset:256
	s_and_b64 vcc, exec, s[16:17]
	s_cbranch_vccz .LBB0_707
	s_waitcnt vmcnt(0)
	s_cmpk_gt_u32 s33, 0xff
	s_cbranch_scc1 .LBB0_717
	s_barrier
